# mix phase: pass 1 of the 8 sample-row tiles moved to workgroups 8..15 (flag + agent-scope sc1 stores/loads for that tile): 5 GEMM units per workgroup at most instead of 6
# speedup vs baseline: 1.0067x; 1.0006x over previous
.LBB0_74:
	v_readlane_b32 s4, v252, 34
	v_readlane_b32 s5, v252, 35
	s_mul_hi_u32 s0, s27, s4
	s_mul_i32 s1, s27, s4
	v_readlane_b32 s4, v251, 0
	s_cmp_eq_u32 s12, 0
	s_cbranch_scc1 .Lmixrb_a
	s_cmp_eq_u32 s27, 2
	s_cbranch_scc0 .Lmixrb_a
	v_readlane_b32 s18, v252, 34
	s_cmp_eq_u32 s18, 0x100
	s_cbranch_scc0 .Lmixrb_a
	s_sub_u32 s4, s4, 8
	s_min_u32 s4, s4, 0x400
.Lmixrb_a:
	s_ashr_i32 s5, s4, 31
	s_add_u32 s4, s1, s4
	s_addc_u32 s5, s0, s5
	v_mov_b64_e32 v[2:3], 0x208
	v_cmp_lt_i64_e64 s[0:1], s[4:5], v[2:3]
	v_mov_b64_e32 v[2:3], 0x207
	v_cmp_gt_i64_e32 vcc, s[4:5], v[2:3]
	s_cbranch_vccnz .LBB0_76
	s_ashr_i32 s5, s4, 31
	s_lshr_b32 s5, s5, 29
	s_add_i32 s5, s4, s5
	s_ashr_i32 s18, s5, 3
	s_and_b32 s5, s5, -8
	s_sub_i32 s4, s4, s5
	s_cmp_lt_i32 s4, 0
	s_movk_i32 s5, 0x42
	s_cselect_b32 s5, s5, 0x41
	s_mul_i32 s4, s5, s4
	s_add_i32 s4, s4, s18
	s_ashr_i32 s5, s4, 31
	s_lshr_b32 s5, s5, 27
	s_add_i32 s5, s4, s5
	s_ashr_i32 s18, s5, 5
	s_lshl_b32 s18, s18, 3
	s_sub_i32 s19, 0x82, s18
	s_min_i32 s19, s19, 8
	s_abs_i32 s20, s19
	v_cvt_f32_u32_e32 v2, s20
	s_sub_i32 s22, 0, s20
	s_andn2_b32 s5, s5, 31
	s_sub_i32 s4, s4, s5
	v_rcp_iflag_f32_e32 v2, v2
	s_abs_i32 s5, s4
	s_xor_b32 s21, s4, s19
	s_ashr_i32 s21, s21, 31
	v_mul_f32_e32 v2, 0x4f7ffffe, v2
	v_cvt_u32_f32_e32 v2, v2
	s_nop 0
	v_readfirstlane_b32 s23, v2
	s_mul_i32 s22, s22, s23
	s_mul_hi_u32 s22, s23, s22
	s_add_i32 s23, s23, s22
	s_mul_hi_u32 s22, s5, s23
	s_mul_i32 s23, s22, s20
	s_sub_i32 s5, s5, s23
	s_add_i32 s35, s22, 1
	s_sub_i32 s23, s5, s20
	s_cmp_ge_u32 s5, s20
	s_cselect_b32 s22, s35, s22
	s_cselect_b32 s5, s23, s5
	s_add_i32 s23, s22, 1
	s_cmp_ge_u32 s5, s20
	s_cselect_b32 s5, s23, s22
	s_xor_b32 s5, s5, s21
	s_sub_i32 s35, s5, s21
	s_mul_i32 s5, s35, s19
	s_sub_i32 s4, s4, s5
	s_add_i32 s36, s4, s18
	s_andn2_b64 vcc, exec, s[0:1]
	s_mov_b64 s[0:1], -1
	s_cbranch_vccnz .LBB0_73
	s_branch .LBB0_77

.LBB0_83:
	s_or_b64 exec, exec, s[18:19]
	s_cmp_eq_u32 s12, 0
	s_cbranch_scc1 .Lmixrb_c
	s_cmp_eq_u32 s27, 2
	s_cbranch_scc0 .Lmixrb_c
	v_readlane_b32 s18, v252, 34
	s_cmp_eq_u32 s18, 0x100
	s_cbranch_scc0 .Lmixrb_c
	v_cmp_eq_u32_e32 vcc, 0, v211
	s_and_saveexec_b64 s[20:21], vcc
	s_cbranch_execz .Lmixrb_c2
	v_readlane_b32 s18, v252, 61
	s_mul_i32 s18, s18, 0x420
	s_add_u32 s18, s18, 0x23f9a508
	s_add_u32 s22, s8, s18
	s_addc_u32 s23, s9, 0
	v_mov_b32_e32 v246, s22
	v_mov_b32_e32 v247, s23
	v_readlane_b32 s18, v251, 0
	s_sub_u32 s18, s18, 8
	s_lshl_b32 s18, 1, s18
	s_mov_b32 s19, 0x100000
.Lmixrb_spin:
	flat_load_dword v248, v[246:247] sc1
	s_waitcnt vmcnt(0) lgkmcnt(0)
	v_readfirstlane_b32 s22, v248
	s_and_b32 s22, s22, s18
	s_cmp_lg_u32 s22, 0
	s_cbranch_scc1 .Lmixrb_c2
	s_sleep 4
	s_sub_u32 s19, s19, 1
	s_cmp_lg_u32 s19, 0
	s_cbranch_scc1 .Lmixrb_spin
.Lmixrb_c2:
	s_or_b64 exec, exec, s[20:21]
	s_barrier
.Lmixrb_c:
	v_lshrrev_b32_e32 v212, 6, v211
	v_lshrrev_b32_e32 v214, 2, v212
	v_and_b32_e32 v212, 3, v212
	v_lshlrev_b32_e32 v214, 6, v214
	v_and_b32_e32 v246, 15, v219
	v_add3_u32 v214, v214, v246, s4
	v_lshrrev_b32_e32 v246, 4, v219
	v_and_b32_e32 v247, 1, v246
	v_lshrrev_b32_e32 v246, 1, v246
	v_lshl_add_u32 v246, v247, 1, v246
	v_lshlrev_b32_e32 v246, 4, v246
	v_lshl_add_u32 v246, v212, 6, v246
	s_lshl_b32 s42, s0, 1
	v_add_u32_e32 v246, s42, v246
	v_mov_b32_e32 v247, 0
	s_mov_b32 s43, 0
	v_mov_b32_e32 v216, v214
	v_mov_b32_e32 v217, 0
	v_lshlrev_b64 v[144:145], 12, v[216:217]
	v_lshlrev_b64 v[146:147], 11, v[216:217]
	v_lshl_add_u64 v[144:145], v[144:145], 0, v[246:247]
	v_lshl_add_u64 v[146:147], v[146:147], 0, v[246:247]
	v_lshl_add_u64 v[144:145], v[144:145], 0, s[16:17]
	v_lshl_add_u64 v[146:147], v[146:147], 0, s[10:11]
	s_cmp_eq_u32 s27, 2
	s_cbranch_scc0 .Lmixrb_d
	v_readlane_b32 s18, v252, 34
	s_cmp_eq_u32 s18, 0x100
	s_cbranch_scc0 .Lmixrb_d
	s_and_b64 vcc, exec, s[12:13]
	s_cbranch_vccnz .Lmix_pass1c
	s_branch .Lmix_pass0c
.Lmixrb_d:
	s_and_b64 vcc, exec, s[12:13]
	s_cbranch_vccnz .Lmix_pass1
	s_mov_b32 s42, 0x0
	v_lshl_add_u64 v[148:149], v[144:145], 0, s[42:43]
	global_load_dwordx4 v[166:169], v[148:149], off offset:0
	s_mov_b32 s42, 0x0
	v_lshl_add_u64 v[150:151], v[146:147], 0, s[42:43]
	s_mov_b32 s42, 0x10000
	v_lshl_add_u64 v[148:149], v[144:145], 0, s[42:43]
	global_load_dwordx4 v[170:173], v[148:149], off offset:0
	s_mov_b32 s42, 0x8000
	v_lshl_add_u64 v[152:153], v[146:147], 0, s[42:43]
	s_mov_b32 s42, 0x20000
	v_lshl_add_u64 v[148:149], v[144:145], 0, s[42:43]
	global_load_dwordx4 v[174:177], v[148:149], off offset:0
	s_mov_b32 s42, 0x10000
	v_lshl_add_u64 v[154:155], v[146:147], 0, s[42:43]
	s_mov_b32 s42, 0x30000
	v_lshl_add_u64 v[148:149], v[144:145], 0, s[42:43]
	global_load_dwordx4 v[178:181], v[148:149], off offset:0
	s_mov_b32 s42, 0x18000
	v_lshl_add_u64 v[156:157], v[146:147], 0, s[42:43]
	s_mov_b32 s42, 0x0
	v_lshl_add_u64 v[148:149], v[144:145], 0, s[42:43]
	global_load_dwordx4 v[182:185], v[148:149], off offset:256
	s_mov_b32 s42, 0x0
	v_lshl_add_u64 v[158:159], v[146:147], 0, s[42:43]
	s_mov_b32 s42, 0x10000
	v_lshl_add_u64 v[148:149], v[144:145], 0, s[42:43]
	global_load_dwordx4 v[186:189], v[148:149], off offset:256
	s_mov_b32 s42, 0x8000
	v_lshl_add_u64 v[160:161], v[146:147], 0, s[42:43]
	s_mov_b32 s42, 0x20000
	v_lshl_add_u64 v[148:149], v[144:145], 0, s[42:43]
	global_load_dwordx4 v[190:193], v[148:149], off offset:256
	s_mov_b32 s42, 0x10000
	v_lshl_add_u64 v[162:163], v[146:147], 0, s[42:43]
	s_mov_b32 s42, 0x30000
	v_lshl_add_u64 v[148:149], v[144:145], 0, s[42:43]
	global_load_dwordx4 v[194:197], v[148:149], off offset:256
	s_mov_b32 s42, 0x18000
	v_lshl_add_u64 v[164:165], v[146:147], 0, s[42:43]
	s_waitcnt vmcnt(7)
	v_permlane16_swap_b32_e32 v166, v168
	v_permlane16_swap_b32_e32 v167, v169
	v_lshlrev_b32_e32 v246, 16, v166
	v_and_b32_e32 v247, 0xffff0000, v166
	v_lshlrev_b32_e32 v248, 16, v167
	v_and_b32_e32 v249, 0xffff0000, v167
	v_pk_mul_f32 v[246:247], v[126:127], v[246:247]
	v_pk_mul_f32 v[248:249], v[128:129], v[248:249]
	v_cvt_pk_bf16_f32 v166, v246, v247
	v_cvt_pk_bf16_f32 v167, v248, v249
	v_lshlrev_b32_e32 v246, 16, v168
	v_and_b32_e32 v247, 0xffff0000, v168
	v_lshlrev_b32_e32 v248, 16, v169
	v_and_b32_e32 v249, 0xffff0000, v169
	v_pk_mul_f32 v[246:247], v[122:123], v[246:247]
	v_pk_mul_f32 v[248:249], v[124:125], v[248:249]
	v_cvt_pk_bf16_f32 v168, v246, v247
	v_cvt_pk_bf16_f32 v169, v248, v249
	s_nop 1
	v_permlane16_swap_b32_e32 v166, v168
	v_permlane16_swap_b32_e32 v167, v169
	global_store_dwordx4 v[150:151], v[166:169], off offset:0
	s_nop 0
	s_mov_b32 s42, 0x80000
	v_lshl_add_u64 v[148:149], v[144:145], 0, s[42:43]
	global_load_dwordx4 v[166:169], v[148:149], off offset:0
	s_mov_b32 s42, 0x40000
	v_lshl_add_u64 v[150:151], v[146:147], 0, s[42:43]
	s_waitcnt vmcnt(8)
	v_permlane16_swap_b32_e32 v170, v172
	v_permlane16_swap_b32_e32 v171, v173
	v_lshlrev_b32_e32 v246, 16, v170
	v_and_b32_e32 v247, 0xffff0000, v170
	v_lshlrev_b32_e32 v248, 16, v171
	v_and_b32_e32 v249, 0xffff0000, v171
	v_pk_mul_f32 v[246:247], v[118:119], v[246:247]
	v_pk_mul_f32 v[248:249], v[120:121], v[248:249]
	v_cvt_pk_bf16_f32 v170, v246, v247
	v_cvt_pk_bf16_f32 v171, v248, v249
	v_lshlrev_b32_e32 v246, 16, v172
	v_and_b32_e32 v247, 0xffff0000, v172
	v_lshlrev_b32_e32 v248, 16, v173
	v_and_b32_e32 v249, 0xffff0000, v173
	v_pk_mul_f32 v[246:247], v[114:115], v[246:247]
	v_pk_mul_f32 v[248:249], v[116:117], v[248:249]
	v_cvt_pk_bf16_f32 v172, v246, v247
	v_cvt_pk_bf16_f32 v173, v248, v249
	s_nop 1
	v_permlane16_swap_b32_e32 v170, v172
	v_permlane16_swap_b32_e32 v171, v173
	global_store_dwordx4 v[152:153], v[170:173], off offset:0
	s_nop 0
	s_mov_b32 s42, 0x90000
	v_lshl_add_u64 v[148:149], v[144:145], 0, s[42:43]
	global_load_dwordx4 v[170:173], v[148:149], off offset:0
	s_mov_b32 s42, 0x48000
	v_lshl_add_u64 v[152:153], v[146:147], 0, s[42:43]
	s_waitcnt vmcnt(9)
	v_permlane16_swap_b32_e32 v174, v176
	v_permlane16_swap_b32_e32 v175, v177
	v_lshlrev_b32_e32 v246, 16, v174
	v_and_b32_e32 v247, 0xffff0000, v174
	v_lshlrev_b32_e32 v248, 16, v175
	v_and_b32_e32 v249, 0xffff0000, v175
	v_pk_mul_f32 v[246:247], v[110:111], v[246:247]
	v_pk_mul_f32 v[248:249], v[112:113], v[248:249]
	v_cvt_pk_bf16_f32 v174, v246, v247
	v_cvt_pk_bf16_f32 v175, v248, v249
	v_lshlrev_b32_e32 v246, 16, v176
	v_and_b32_e32 v247, 0xffff0000, v176
	v_lshlrev_b32_e32 v248, 16, v177
	v_and_b32_e32 v249, 0xffff0000, v177
	v_pk_mul_f32 v[246:247], v[106:107], v[246:247]
	v_pk_mul_f32 v[248:249], v[108:109], v[248:249]
	v_cvt_pk_bf16_f32 v176, v246, v247
	v_cvt_pk_bf16_f32 v177, v248, v249
	s_nop 1
	v_permlane16_swap_b32_e32 v174, v176
	v_permlane16_swap_b32_e32 v175, v177
	global_store_dwordx4 v[154:155], v[174:177], off offset:0
	s_nop 0
	s_mov_b32 s42, 0xa0000
	v_lshl_add_u64 v[148:149], v[144:145], 0, s[42:43]
	global_load_dwordx4 v[174:177], v[148:149], off offset:0
	s_mov_b32 s42, 0x50000
	v_lshl_add_u64 v[154:155], v[146:147], 0, s[42:43]
	s_waitcnt vmcnt(10)
	v_permlane16_swap_b32_e32 v178, v180
	v_permlane16_swap_b32_e32 v179, v181
	v_lshlrev_b32_e32 v246, 16, v178
	v_and_b32_e32 v247, 0xffff0000, v178
	v_lshlrev_b32_e32 v248, 16, v179
	v_and_b32_e32 v249, 0xffff0000, v179
	v_pk_mul_f32 v[246:247], v[102:103], v[246:247]
	v_pk_mul_f32 v[248:249], v[104:105], v[248:249]
	v_cvt_pk_bf16_f32 v178, v246, v247
	v_cvt_pk_bf16_f32 v179, v248, v249
	v_lshlrev_b32_e32 v246, 16, v180
	v_and_b32_e32 v247, 0xffff0000, v180
	v_lshlrev_b32_e32 v248, 16, v181
	v_and_b32_e32 v249, 0xffff0000, v181
	v_pk_mul_f32 v[246:247], v[98:99], v[246:247]
	v_pk_mul_f32 v[248:249], v[100:101], v[248:249]
	v_cvt_pk_bf16_f32 v180, v246, v247
	v_cvt_pk_bf16_f32 v181, v248, v249
	s_nop 1
	v_permlane16_swap_b32_e32 v178, v180
	v_permlane16_swap_b32_e32 v179, v181
	global_store_dwordx4 v[156:157], v[178:181], off offset:0
	s_nop 0
	s_mov_b32 s42, 0xb0000
	v_lshl_add_u64 v[148:149], v[144:145], 0, s[42:43]
	global_load_dwordx4 v[178:181], v[148:149], off offset:0
	s_mov_b32 s42, 0x58000
	v_lshl_add_u64 v[156:157], v[146:147], 0, s[42:43]
	s_waitcnt vmcnt(11)
	v_permlane16_swap_b32_e32 v182, v184
	v_permlane16_swap_b32_e32 v183, v185
	v_lshlrev_b32_e32 v246, 16, v182
	v_and_b32_e32 v247, 0xffff0000, v182
	v_lshlrev_b32_e32 v248, 16, v183
	v_and_b32_e32 v249, 0xffff0000, v183
	v_pk_mul_f32 v[246:247], v[94:95], v[246:247]
	v_pk_mul_f32 v[248:249], v[96:97], v[248:249]
	v_cvt_pk_bf16_f32 v182, v246, v247
	v_cvt_pk_bf16_f32 v183, v248, v249
	v_lshlrev_b32_e32 v246, 16, v184
	v_and_b32_e32 v247, 0xffff0000, v184
	v_lshlrev_b32_e32 v248, 16, v185
	v_and_b32_e32 v249, 0xffff0000, v185
	v_pk_mul_f32 v[246:247], v[90:91], v[246:247]
	v_pk_mul_f32 v[248:249], v[92:93], v[248:249]
	v_cvt_pk_bf16_f32 v184, v246, v247
	v_cvt_pk_bf16_f32 v185, v248, v249
	s_nop 1
	v_permlane16_swap_b32_e32 v182, v184
	v_permlane16_swap_b32_e32 v183, v185
	global_store_dwordx4 v[158:159], v[182:185], off offset:256
	s_nop 0
	s_mov_b32 s42, 0x80000
	v_lshl_add_u64 v[148:149], v[144:145], 0, s[42:43]
	global_load_dwordx4 v[182:185], v[148:149], off offset:256
	s_mov_b32 s42, 0x40000
	v_lshl_add_u64 v[158:159], v[146:147], 0, s[42:43]
	s_waitcnt vmcnt(12)
	v_permlane16_swap_b32_e32 v186, v188
	v_permlane16_swap_b32_e32 v187, v189
	v_lshlrev_b32_e32 v246, 16, v186
	v_and_b32_e32 v247, 0xffff0000, v186
	v_lshlrev_b32_e32 v248, 16, v187
	v_and_b32_e32 v249, 0xffff0000, v187
	v_pk_mul_f32 v[246:247], v[86:87], v[246:247]
	v_pk_mul_f32 v[248:249], v[88:89], v[248:249]
	v_cvt_pk_bf16_f32 v186, v246, v247
	v_cvt_pk_bf16_f32 v187, v248, v249
	v_lshlrev_b32_e32 v246, 16, v188
	v_and_b32_e32 v247, 0xffff0000, v188
	v_lshlrev_b32_e32 v248, 16, v189
	v_and_b32_e32 v249, 0xffff0000, v189
	v_pk_mul_f32 v[246:247], v[82:83], v[246:247]
	v_pk_mul_f32 v[248:249], v[84:85], v[248:249]
	v_cvt_pk_bf16_f32 v188, v246, v247
	v_cvt_pk_bf16_f32 v189, v248, v249
	s_nop 1
	v_permlane16_swap_b32_e32 v186, v188
	v_permlane16_swap_b32_e32 v187, v189
	global_store_dwordx4 v[160:161], v[186:189], off offset:256
	s_nop 0
	s_mov_b32 s42, 0x90000
	v_lshl_add_u64 v[148:149], v[144:145], 0, s[42:43]
	global_load_dwordx4 v[186:189], v[148:149], off offset:256
	s_mov_b32 s42, 0x48000
	v_lshl_add_u64 v[160:161], v[146:147], 0, s[42:43]
	s_waitcnt vmcnt(13)
	v_permlane16_swap_b32_e32 v190, v192
	v_permlane16_swap_b32_e32 v191, v193
	v_lshlrev_b32_e32 v246, 16, v190
	v_and_b32_e32 v247, 0xffff0000, v190
	v_lshlrev_b32_e32 v248, 16, v191
	v_and_b32_e32 v249, 0xffff0000, v191
	v_pk_mul_f32 v[246:247], v[78:79], v[246:247]
	v_pk_mul_f32 v[248:249], v[80:81], v[248:249]
	v_cvt_pk_bf16_f32 v190, v246, v247
	v_cvt_pk_bf16_f32 v191, v248, v249
	v_lshlrev_b32_e32 v246, 16, v192
	v_and_b32_e32 v247, 0xffff0000, v192
	v_lshlrev_b32_e32 v248, 16, v193
	v_and_b32_e32 v249, 0xffff0000, v193
	v_pk_mul_f32 v[246:247], v[74:75], v[246:247]
	v_pk_mul_f32 v[248:249], v[76:77], v[248:249]
	v_cvt_pk_bf16_f32 v192, v246, v247
	v_cvt_pk_bf16_f32 v193, v248, v249
	s_nop 1
	v_permlane16_swap_b32_e32 v190, v192
	v_permlane16_swap_b32_e32 v191, v193
	global_store_dwordx4 v[162:163], v[190:193], off offset:256
	s_nop 0
	s_mov_b32 s42, 0xa0000
	v_lshl_add_u64 v[148:149], v[144:145], 0, s[42:43]
	global_load_dwordx4 v[190:193], v[148:149], off offset:256
	s_mov_b32 s42, 0x50000
	v_lshl_add_u64 v[162:163], v[146:147], 0, s[42:43]
	s_waitcnt vmcnt(14)
	v_permlane16_swap_b32_e32 v194, v196
	v_permlane16_swap_b32_e32 v195, v197
	v_lshlrev_b32_e32 v246, 16, v194
	v_and_b32_e32 v247, 0xffff0000, v194
	v_lshlrev_b32_e32 v248, 16, v195
	v_and_b32_e32 v249, 0xffff0000, v195
	v_pk_mul_f32 v[246:247], v[70:71], v[246:247]
	v_pk_mul_f32 v[248:249], v[72:73], v[248:249]
	v_cvt_pk_bf16_f32 v194, v246, v247
	v_cvt_pk_bf16_f32 v195, v248, v249
	v_lshlrev_b32_e32 v246, 16, v196
	v_and_b32_e32 v247, 0xffff0000, v196
	v_lshlrev_b32_e32 v248, 16, v197
	v_and_b32_e32 v249, 0xffff0000, v197
	v_pk_mul_f32 v[246:247], v[66:67], v[246:247]
	v_pk_mul_f32 v[248:249], v[68:69], v[248:249]
	v_cvt_pk_bf16_f32 v196, v246, v247
	v_cvt_pk_bf16_f32 v197, v248, v249
	s_nop 1
	v_permlane16_swap_b32_e32 v194, v196
	v_permlane16_swap_b32_e32 v195, v197
	global_store_dwordx4 v[164:165], v[194:197], off offset:256
	s_nop 0
	s_mov_b32 s42, 0xb0000
	v_lshl_add_u64 v[148:149], v[144:145], 0, s[42:43]
	global_load_dwordx4 v[194:197], v[148:149], off offset:256
	s_mov_b32 s42, 0x58000
	v_lshl_add_u64 v[164:165], v[146:147], 0, s[42:43]
	s_waitcnt vmcnt(14)
	v_permlane16_swap_b32_e32 v166, v168
	v_permlane16_swap_b32_e32 v167, v169
	v_lshlrev_b32_e32 v246, 16, v166
	v_and_b32_e32 v247, 0xffff0000, v166
	v_lshlrev_b32_e32 v248, 16, v167
	v_and_b32_e32 v249, 0xffff0000, v167
	v_pk_mul_f32 v[246:247], v[62:63], v[246:247]
	v_pk_mul_f32 v[248:249], v[64:65], v[248:249]
	v_cvt_pk_bf16_f32 v166, v246, v247
	v_cvt_pk_bf16_f32 v167, v248, v249
	v_lshlrev_b32_e32 v246, 16, v168
	v_and_b32_e32 v247, 0xffff0000, v168
	v_lshlrev_b32_e32 v248, 16, v169
	v_and_b32_e32 v249, 0xffff0000, v169
	v_pk_mul_f32 v[246:247], v[58:59], v[246:247]
	v_pk_mul_f32 v[248:249], v[60:61], v[248:249]
	v_cvt_pk_bf16_f32 v168, v246, v247
	v_cvt_pk_bf16_f32 v169, v248, v249
	s_nop 1
	v_permlane16_swap_b32_e32 v166, v168
	v_permlane16_swap_b32_e32 v167, v169
	global_store_dwordx4 v[150:151], v[166:169], off offset:0
	s_waitcnt vmcnt(13)
	v_permlane16_swap_b32_e32 v170, v172
	v_permlane16_swap_b32_e32 v171, v173
	v_lshlrev_b32_e32 v246, 16, v170
	v_and_b32_e32 v247, 0xffff0000, v170
	v_lshlrev_b32_e32 v248, 16, v171
	v_and_b32_e32 v249, 0xffff0000, v171
	v_pk_mul_f32 v[246:247], v[54:55], v[246:247]
	v_pk_mul_f32 v[248:249], v[56:57], v[248:249]
	v_cvt_pk_bf16_f32 v170, v246, v247
	v_cvt_pk_bf16_f32 v171, v248, v249
	v_lshlrev_b32_e32 v246, 16, v172
	v_and_b32_e32 v247, 0xffff0000, v172
	v_lshlrev_b32_e32 v248, 16, v173
	v_and_b32_e32 v249, 0xffff0000, v173
	v_pk_mul_f32 v[246:247], v[50:51], v[246:247]
	v_pk_mul_f32 v[248:249], v[52:53], v[248:249]
	v_cvt_pk_bf16_f32 v172, v246, v247
	v_cvt_pk_bf16_f32 v173, v248, v249
	s_nop 1
	v_permlane16_swap_b32_e32 v170, v172
	v_permlane16_swap_b32_e32 v171, v173
	global_store_dwordx4 v[152:153], v[170:173], off offset:0
	s_waitcnt vmcnt(12)
	v_permlane16_swap_b32_e32 v174, v176
	v_permlane16_swap_b32_e32 v175, v177
	v_lshlrev_b32_e32 v246, 16, v174
	v_and_b32_e32 v247, 0xffff0000, v174
	v_lshlrev_b32_e32 v248, 16, v175
	v_and_b32_e32 v249, 0xffff0000, v175
	v_pk_mul_f32 v[246:247], v[46:47], v[246:247]
	v_pk_mul_f32 v[248:249], v[48:49], v[248:249]
	v_cvt_pk_bf16_f32 v174, v246, v247
	v_cvt_pk_bf16_f32 v175, v248, v249
	v_lshlrev_b32_e32 v246, 16, v176
	v_and_b32_e32 v247, 0xffff0000, v176
	v_lshlrev_b32_e32 v248, 16, v177
	v_and_b32_e32 v249, 0xffff0000, v177
	v_pk_mul_f32 v[246:247], v[42:43], v[246:247]
	v_pk_mul_f32 v[248:249], v[44:45], v[248:249]
	v_cvt_pk_bf16_f32 v176, v246, v247
	v_cvt_pk_bf16_f32 v177, v248, v249
	s_nop 1
	v_permlane16_swap_b32_e32 v174, v176
	v_permlane16_swap_b32_e32 v175, v177
	global_store_dwordx4 v[154:155], v[174:177], off offset:0
	s_waitcnt vmcnt(11)
	v_permlane16_swap_b32_e32 v178, v180
	v_permlane16_swap_b32_e32 v179, v181
	v_lshlrev_b32_e32 v246, 16, v178
	v_and_b32_e32 v247, 0xffff0000, v178
	v_lshlrev_b32_e32 v248, 16, v179
	v_and_b32_e32 v249, 0xffff0000, v179
	v_pk_mul_f32 v[246:247], v[38:39], v[246:247]
	v_pk_mul_f32 v[248:249], v[40:41], v[248:249]
	v_cvt_pk_bf16_f32 v178, v246, v247
	v_cvt_pk_bf16_f32 v179, v248, v249
	v_lshlrev_b32_e32 v246, 16, v180
	v_and_b32_e32 v247, 0xffff0000, v180
	v_lshlrev_b32_e32 v248, 16, v181
	v_and_b32_e32 v249, 0xffff0000, v181
	v_pk_mul_f32 v[246:247], v[34:35], v[246:247]
	v_pk_mul_f32 v[248:249], v[36:37], v[248:249]
	v_cvt_pk_bf16_f32 v180, v246, v247
	v_cvt_pk_bf16_f32 v181, v248, v249
	s_nop 1
	v_permlane16_swap_b32_e32 v178, v180
	v_permlane16_swap_b32_e32 v179, v181
	global_store_dwordx4 v[156:157], v[178:181], off offset:0
	s_waitcnt vmcnt(10)
	v_permlane16_swap_b32_e32 v182, v184
	v_permlane16_swap_b32_e32 v183, v185
	v_lshlrev_b32_e32 v246, 16, v182
	v_and_b32_e32 v247, 0xffff0000, v182
	v_lshlrev_b32_e32 v248, 16, v183
	v_and_b32_e32 v249, 0xffff0000, v183
	v_pk_mul_f32 v[246:247], v[30:31], v[246:247]
	v_pk_mul_f32 v[248:249], v[32:33], v[248:249]
	v_cvt_pk_bf16_f32 v182, v246, v247
	v_cvt_pk_bf16_f32 v183, v248, v249
	v_lshlrev_b32_e32 v246, 16, v184
	v_and_b32_e32 v247, 0xffff0000, v184
	v_lshlrev_b32_e32 v248, 16, v185
	v_and_b32_e32 v249, 0xffff0000, v185
	v_pk_mul_f32 v[246:247], v[26:27], v[246:247]
	v_pk_mul_f32 v[248:249], v[28:29], v[248:249]
	v_cvt_pk_bf16_f32 v184, v246, v247
	v_cvt_pk_bf16_f32 v185, v248, v249
	s_nop 1
	v_permlane16_swap_b32_e32 v182, v184
	v_permlane16_swap_b32_e32 v183, v185
	global_store_dwordx4 v[158:159], v[182:185], off offset:256
	s_waitcnt vmcnt(9)
	v_permlane16_swap_b32_e32 v186, v188
	v_permlane16_swap_b32_e32 v187, v189
	v_lshlrev_b32_e32 v246, 16, v186
	v_and_b32_e32 v247, 0xffff0000, v186
	v_lshlrev_b32_e32 v248, 16, v187
	v_and_b32_e32 v249, 0xffff0000, v187
	v_pk_mul_f32 v[246:247], v[22:23], v[246:247]
	v_pk_mul_f32 v[248:249], v[24:25], v[248:249]
	v_cvt_pk_bf16_f32 v186, v246, v247
	v_cvt_pk_bf16_f32 v187, v248, v249
	v_lshlrev_b32_e32 v246, 16, v188
	v_and_b32_e32 v247, 0xffff0000, v188
	v_lshlrev_b32_e32 v248, 16, v189
	v_and_b32_e32 v249, 0xffff0000, v189
	v_pk_mul_f32 v[246:247], v[18:19], v[246:247]
	v_pk_mul_f32 v[248:249], v[20:21], v[248:249]
	v_cvt_pk_bf16_f32 v188, v246, v247
	v_cvt_pk_bf16_f32 v189, v248, v249
	s_nop 1
	v_permlane16_swap_b32_e32 v186, v188
	v_permlane16_swap_b32_e32 v187, v189
	global_store_dwordx4 v[160:161], v[186:189], off offset:256
	s_waitcnt vmcnt(8)
	v_permlane16_swap_b32_e32 v190, v192
	v_permlane16_swap_b32_e32 v191, v193
	v_lshlrev_b32_e32 v246, 16, v190
	v_and_b32_e32 v247, 0xffff0000, v190
	v_lshlrev_b32_e32 v248, 16, v191
	v_and_b32_e32 v249, 0xffff0000, v191
	v_pk_mul_f32 v[246:247], v[14:15], v[246:247]
	v_pk_mul_f32 v[248:249], v[16:17], v[248:249]
	v_cvt_pk_bf16_f32 v190, v246, v247
	v_cvt_pk_bf16_f32 v191, v248, v249
	v_lshlrev_b32_e32 v246, 16, v192
	v_and_b32_e32 v247, 0xffff0000, v192
	v_lshlrev_b32_e32 v248, 16, v193
	v_and_b32_e32 v249, 0xffff0000, v193
	v_pk_mul_f32 v[246:247], v[10:11], v[246:247]
	v_pk_mul_f32 v[248:249], v[12:13], v[248:249]
	v_cvt_pk_bf16_f32 v192, v246, v247
	v_cvt_pk_bf16_f32 v193, v248, v249
	s_nop 1
	v_permlane16_swap_b32_e32 v190, v192
	v_permlane16_swap_b32_e32 v191, v193
	global_store_dwordx4 v[162:163], v[190:193], off offset:256
	s_waitcnt vmcnt(7)
	v_permlane16_swap_b32_e32 v194, v196
	v_permlane16_swap_b32_e32 v195, v197
	v_lshlrev_b32_e32 v246, 16, v194
	v_and_b32_e32 v247, 0xffff0000, v194
	v_lshlrev_b32_e32 v248, 16, v195
	v_and_b32_e32 v249, 0xffff0000, v195
	v_pk_mul_f32 v[246:247], v[6:7], v[246:247]
	v_pk_mul_f32 v[248:249], v[8:9], v[248:249]
	v_cvt_pk_bf16_f32 v194, v246, v247
	v_cvt_pk_bf16_f32 v195, v248, v249
	v_lshlrev_b32_e32 v246, 16, v196
	v_and_b32_e32 v247, 0xffff0000, v196
	v_lshlrev_b32_e32 v248, 16, v197
	v_and_b32_e32 v249, 0xffff0000, v197
	v_pk_mul_f32 v[246:247], v[2:3], v[246:247]
	v_pk_mul_f32 v[248:249], v[4:5], v[248:249]
	v_cvt_pk_bf16_f32 v196, v246, v247
	v_cvt_pk_bf16_f32 v197, v248, v249
	s_nop 1
	v_permlane16_swap_b32_e32 v194, v196
	v_permlane16_swap_b32_e32 v195, v197
	global_store_dwordx4 v[164:165], v[194:197], off offset:256
	s_branch .Lmix_done
.Lmix_pass1:
	s_mov_b32 s42, 0x0
	v_lshl_add_u64 v[148:149], v[144:145], 0, s[42:43]
	global_load_dwordx4 v[166:169], v[148:149], off offset:0
	s_mov_b32 s42, 0x0
	v_lshl_add_u64 v[150:151], v[146:147], 0, s[42:43]
	global_load_dwordx4 v[198:201], v[150:151], off offset:0
	s_mov_b32 s42, 0x10000
	v_lshl_add_u64 v[148:149], v[144:145], 0, s[42:43]
	global_load_dwordx4 v[170:173], v[148:149], off offset:0
	s_mov_b32 s42, 0x8000
	v_lshl_add_u64 v[152:153], v[146:147], 0, s[42:43]
	global_load_dwordx4 v[202:205], v[152:153], off offset:0
	s_mov_b32 s42, 0x20000
	v_lshl_add_u64 v[148:149], v[144:145], 0, s[42:43]
	global_load_dwordx4 v[174:177], v[148:149], off offset:0
	s_mov_b32 s42, 0x10000
	v_lshl_add_u64 v[154:155], v[146:147], 0, s[42:43]
	global_load_dwordx4 v[206:209], v[154:155], off offset:0
	s_mov_b32 s42, 0x30000
	v_lshl_add_u64 v[148:149], v[144:145], 0, s[42:43]
	global_load_dwordx4 v[178:181], v[148:149], off offset:0
	s_mov_b32 s42, 0x18000
	v_lshl_add_u64 v[156:157], v[146:147], 0, s[42:43]
	global_load_dwordx4 v[226:229], v[156:157], off offset:0
	s_mov_b32 s42, 0x0
	v_lshl_add_u64 v[148:149], v[144:145], 0, s[42:43]
	global_load_dwordx4 v[182:185], v[148:149], off offset:256
	s_mov_b32 s42, 0x0
	v_lshl_add_u64 v[158:159], v[146:147], 0, s[42:43]
	global_load_dwordx4 v[230:233], v[158:159], off offset:256
	s_mov_b32 s42, 0x10000
	v_lshl_add_u64 v[148:149], v[144:145], 0, s[42:43]
	global_load_dwordx4 v[186:189], v[148:149], off offset:256
	s_mov_b32 s42, 0x8000
	v_lshl_add_u64 v[160:161], v[146:147], 0, s[42:43]
	global_load_dwordx4 v[234:237], v[160:161], off offset:256
	s_mov_b32 s42, 0x20000
	v_lshl_add_u64 v[148:149], v[144:145], 0, s[42:43]
	global_load_dwordx4 v[190:193], v[148:149], off offset:256
	s_mov_b32 s42, 0x10000
	v_lshl_add_u64 v[162:163], v[146:147], 0, s[42:43]
	global_load_dwordx4 v[238:241], v[162:163], off offset:256
	s_mov_b32 s42, 0x30000
	v_lshl_add_u64 v[148:149], v[144:145], 0, s[42:43]
	global_load_dwordx4 v[194:197], v[148:149], off offset:256
	s_mov_b32 s42, 0x18000
	v_lshl_add_u64 v[164:165], v[146:147], 0, s[42:43]
	global_load_dwordx4 v[242:245], v[164:165], off offset:256
	s_waitcnt vmcnt(14)
	v_permlane16_swap_b32_e32 v166, v168
	v_permlane16_swap_b32_e32 v167, v169
	v_permlane16_swap_b32_e32 v198, v200
	v_permlane16_swap_b32_e32 v199, v201
	v_lshlrev_b32_e32 v246, 16, v166
	v_and_b32_e32 v247, 0xffff0000, v166
	v_lshlrev_b32_e32 v248, 16, v167
	v_and_b32_e32 v249, 0xffff0000, v167
	v_pk_mul_f32 v[246:247], v[126:127], v[246:247]
	v_pk_mul_f32 v[248:249], v[128:129], v[248:249]
	v_lshlrev_b32_e32 v216, 16, v198
	v_and_b32_e32 v217, 0xffff0000, v198
	v_lshlrev_b32_e32 v220, 16, v199
	v_and_b32_e32 v221, 0xffff0000, v199
	v_pk_add_f32 v[246:247], v[246:247], v[216:217]
	v_pk_add_f32 v[248:249], v[248:249], v[220:221]
	v_cvt_pk_bf16_f32 v166, v246, v247
	v_cvt_pk_bf16_f32 v167, v248, v249
	v_lshlrev_b32_e32 v246, 16, v168
	v_and_b32_e32 v247, 0xffff0000, v168
	v_lshlrev_b32_e32 v248, 16, v169
	v_and_b32_e32 v249, 0xffff0000, v169
	v_pk_mul_f32 v[246:247], v[122:123], v[246:247]
	v_pk_mul_f32 v[248:249], v[124:125], v[248:249]
	v_lshlrev_b32_e32 v216, 16, v200
	v_and_b32_e32 v217, 0xffff0000, v200
	v_lshlrev_b32_e32 v220, 16, v201
	v_and_b32_e32 v221, 0xffff0000, v201
	v_pk_add_f32 v[246:247], v[246:247], v[216:217]
	v_pk_add_f32 v[248:249], v[248:249], v[220:221]
	v_cvt_pk_bf16_f32 v168, v246, v247
	v_cvt_pk_bf16_f32 v169, v248, v249
	s_nop 1
	v_permlane16_swap_b32_e32 v166, v168
	v_permlane16_swap_b32_e32 v167, v169
	global_store_dwordx4 v[150:151], v[166:169], off offset:0
	s_nop 0
	s_mov_b32 s42, 0x80000
	v_lshl_add_u64 v[148:149], v[144:145], 0, s[42:43]
	global_load_dwordx4 v[166:169], v[148:149], off offset:0
	s_mov_b32 s42, 0x40000
	v_lshl_add_u64 v[150:151], v[146:147], 0, s[42:43]
	global_load_dwordx4 v[198:201], v[150:151], off offset:0
	s_waitcnt vmcnt(15)
	v_permlane16_swap_b32_e32 v170, v172
	v_permlane16_swap_b32_e32 v171, v173
	v_permlane16_swap_b32_e32 v202, v204
	v_permlane16_swap_b32_e32 v203, v205
	v_lshlrev_b32_e32 v246, 16, v170
	v_and_b32_e32 v247, 0xffff0000, v170
	v_lshlrev_b32_e32 v248, 16, v171
	v_and_b32_e32 v249, 0xffff0000, v171
	v_pk_mul_f32 v[246:247], v[118:119], v[246:247]
	v_pk_mul_f32 v[248:249], v[120:121], v[248:249]
	v_lshlrev_b32_e32 v216, 16, v202
	v_and_b32_e32 v217, 0xffff0000, v202
	v_lshlrev_b32_e32 v220, 16, v203
	v_and_b32_e32 v221, 0xffff0000, v203
	v_pk_add_f32 v[246:247], v[246:247], v[216:217]
	v_pk_add_f32 v[248:249], v[248:249], v[220:221]
	v_cvt_pk_bf16_f32 v170, v246, v247
	v_cvt_pk_bf16_f32 v171, v248, v249
	v_lshlrev_b32_e32 v246, 16, v172
	v_and_b32_e32 v247, 0xffff0000, v172
	v_lshlrev_b32_e32 v248, 16, v173
	v_and_b32_e32 v249, 0xffff0000, v173
	v_pk_mul_f32 v[246:247], v[114:115], v[246:247]
	v_pk_mul_f32 v[248:249], v[116:117], v[248:249]
	v_lshlrev_b32_e32 v216, 16, v204
	v_and_b32_e32 v217, 0xffff0000, v204
	v_lshlrev_b32_e32 v220, 16, v205
	v_and_b32_e32 v221, 0xffff0000, v205
	v_pk_add_f32 v[246:247], v[246:247], v[216:217]
	v_pk_add_f32 v[248:249], v[248:249], v[220:221]
	v_cvt_pk_bf16_f32 v172, v246, v247
	v_cvt_pk_bf16_f32 v173, v248, v249
	s_nop 1
	v_permlane16_swap_b32_e32 v170, v172
	v_permlane16_swap_b32_e32 v171, v173
	global_store_dwordx4 v[152:153], v[170:173], off offset:0
	s_nop 0
	s_mov_b32 s42, 0x90000
	v_lshl_add_u64 v[148:149], v[144:145], 0, s[42:43]
	global_load_dwordx4 v[170:173], v[148:149], off offset:0
	s_mov_b32 s42, 0x48000
	v_lshl_add_u64 v[152:153], v[146:147], 0, s[42:43]
	global_load_dwordx4 v[202:205], v[152:153], off offset:0
	s_waitcnt vmcnt(16)
	v_permlane16_swap_b32_e32 v174, v176
	v_permlane16_swap_b32_e32 v175, v177
	v_permlane16_swap_b32_e32 v206, v208
	v_permlane16_swap_b32_e32 v207, v209
	v_lshlrev_b32_e32 v246, 16, v174
	v_and_b32_e32 v247, 0xffff0000, v174
	v_lshlrev_b32_e32 v248, 16, v175
	v_and_b32_e32 v249, 0xffff0000, v175
	v_pk_mul_f32 v[246:247], v[110:111], v[246:247]
	v_pk_mul_f32 v[248:249], v[112:113], v[248:249]
	v_lshlrev_b32_e32 v216, 16, v206
	v_and_b32_e32 v217, 0xffff0000, v206
	v_lshlrev_b32_e32 v220, 16, v207
	v_and_b32_e32 v221, 0xffff0000, v207
	v_pk_add_f32 v[246:247], v[246:247], v[216:217]
	v_pk_add_f32 v[248:249], v[248:249], v[220:221]
	v_cvt_pk_bf16_f32 v174, v246, v247
	v_cvt_pk_bf16_f32 v175, v248, v249
	v_lshlrev_b32_e32 v246, 16, v176
	v_and_b32_e32 v247, 0xffff0000, v176
	v_lshlrev_b32_e32 v248, 16, v177
	v_and_b32_e32 v249, 0xffff0000, v177
	v_pk_mul_f32 v[246:247], v[106:107], v[246:247]
	v_pk_mul_f32 v[248:249], v[108:109], v[248:249]
	v_lshlrev_b32_e32 v216, 16, v208
	v_and_b32_e32 v217, 0xffff0000, v208
	v_lshlrev_b32_e32 v220, 16, v209
	v_and_b32_e32 v221, 0xffff0000, v209
	v_pk_add_f32 v[246:247], v[246:247], v[216:217]
	v_pk_add_f32 v[248:249], v[248:249], v[220:221]
	v_cvt_pk_bf16_f32 v176, v246, v247
	v_cvt_pk_bf16_f32 v177, v248, v249
	s_nop 1
	v_permlane16_swap_b32_e32 v174, v176
	v_permlane16_swap_b32_e32 v175, v177
	global_store_dwordx4 v[154:155], v[174:177], off offset:0
	s_nop 0
	s_mov_b32 s42, 0xa0000
	v_lshl_add_u64 v[148:149], v[144:145], 0, s[42:43]
	global_load_dwordx4 v[174:177], v[148:149], off offset:0
	s_mov_b32 s42, 0x50000
	v_lshl_add_u64 v[154:155], v[146:147], 0, s[42:43]
	global_load_dwordx4 v[206:209], v[154:155], off offset:0
	s_waitcnt vmcnt(17)
	v_permlane16_swap_b32_e32 v178, v180
	v_permlane16_swap_b32_e32 v179, v181
	v_permlane16_swap_b32_e32 v226, v228
	v_permlane16_swap_b32_e32 v227, v229
	v_lshlrev_b32_e32 v246, 16, v178
	v_and_b32_e32 v247, 0xffff0000, v178
	v_lshlrev_b32_e32 v248, 16, v179
	v_and_b32_e32 v249, 0xffff0000, v179
	v_pk_mul_f32 v[246:247], v[102:103], v[246:247]
	v_pk_mul_f32 v[248:249], v[104:105], v[248:249]
	v_lshlrev_b32_e32 v216, 16, v226
	v_and_b32_e32 v217, 0xffff0000, v226
	v_lshlrev_b32_e32 v220, 16, v227
	v_and_b32_e32 v221, 0xffff0000, v227
	v_pk_add_f32 v[246:247], v[246:247], v[216:217]
	v_pk_add_f32 v[248:249], v[248:249], v[220:221]
	v_cvt_pk_bf16_f32 v178, v246, v247
	v_cvt_pk_bf16_f32 v179, v248, v249
	v_lshlrev_b32_e32 v246, 16, v180
	v_and_b32_e32 v247, 0xffff0000, v180
	v_lshlrev_b32_e32 v248, 16, v181
	v_and_b32_e32 v249, 0xffff0000, v181
	v_pk_mul_f32 v[246:247], v[98:99], v[246:247]
	v_pk_mul_f32 v[248:249], v[100:101], v[248:249]
	v_lshlrev_b32_e32 v216, 16, v228
	v_and_b32_e32 v217, 0xffff0000, v228
	v_lshlrev_b32_e32 v220, 16, v229
	v_and_b32_e32 v221, 0xffff0000, v229
	v_pk_add_f32 v[246:247], v[246:247], v[216:217]
	v_pk_add_f32 v[248:249], v[248:249], v[220:221]
	v_cvt_pk_bf16_f32 v180, v246, v247
	v_cvt_pk_bf16_f32 v181, v248, v249
	s_nop 1
	v_permlane16_swap_b32_e32 v178, v180
	v_permlane16_swap_b32_e32 v179, v181
	global_store_dwordx4 v[156:157], v[178:181], off offset:0
	s_nop 0
	s_mov_b32 s42, 0xb0000
	v_lshl_add_u64 v[148:149], v[144:145], 0, s[42:43]
	global_load_dwordx4 v[178:181], v[148:149], off offset:0
	s_mov_b32 s42, 0x58000
	v_lshl_add_u64 v[156:157], v[146:147], 0, s[42:43]
	global_load_dwordx4 v[226:229], v[156:157], off offset:0
	s_waitcnt vmcnt(18)
	v_permlane16_swap_b32_e32 v182, v184
	v_permlane16_swap_b32_e32 v183, v185
	v_permlane16_swap_b32_e32 v230, v232
	v_permlane16_swap_b32_e32 v231, v233
	v_lshlrev_b32_e32 v246, 16, v182
	v_and_b32_e32 v247, 0xffff0000, v182
	v_lshlrev_b32_e32 v248, 16, v183
	v_and_b32_e32 v249, 0xffff0000, v183
	v_pk_mul_f32 v[246:247], v[94:95], v[246:247]
	v_pk_mul_f32 v[248:249], v[96:97], v[248:249]
	v_lshlrev_b32_e32 v216, 16, v230
	v_and_b32_e32 v217, 0xffff0000, v230
	v_lshlrev_b32_e32 v220, 16, v231
	v_and_b32_e32 v221, 0xffff0000, v231
	v_pk_add_f32 v[246:247], v[246:247], v[216:217]
	v_pk_add_f32 v[248:249], v[248:249], v[220:221]
	v_cvt_pk_bf16_f32 v182, v246, v247
	v_cvt_pk_bf16_f32 v183, v248, v249
	v_lshlrev_b32_e32 v246, 16, v184
	v_and_b32_e32 v247, 0xffff0000, v184
	v_lshlrev_b32_e32 v248, 16, v185
	v_and_b32_e32 v249, 0xffff0000, v185
	v_pk_mul_f32 v[246:247], v[90:91], v[246:247]
	v_pk_mul_f32 v[248:249], v[92:93], v[248:249]
	v_lshlrev_b32_e32 v216, 16, v232
	v_and_b32_e32 v217, 0xffff0000, v232
	v_lshlrev_b32_e32 v220, 16, v233
	v_and_b32_e32 v221, 0xffff0000, v233
	v_pk_add_f32 v[246:247], v[246:247], v[216:217]
	v_pk_add_f32 v[248:249], v[248:249], v[220:221]
	v_cvt_pk_bf16_f32 v184, v246, v247
	v_cvt_pk_bf16_f32 v185, v248, v249
	s_nop 1
	v_permlane16_swap_b32_e32 v182, v184
	v_permlane16_swap_b32_e32 v183, v185
	global_store_dwordx4 v[158:159], v[182:185], off offset:256
	s_nop 0
	s_mov_b32 s42, 0x80000
	v_lshl_add_u64 v[148:149], v[144:145], 0, s[42:43]
	global_load_dwordx4 v[182:185], v[148:149], off offset:256
	s_mov_b32 s42, 0x40000
	v_lshl_add_u64 v[158:159], v[146:147], 0, s[42:43]
	global_load_dwordx4 v[230:233], v[158:159], off offset:256
	s_waitcnt vmcnt(19)
	v_permlane16_swap_b32_e32 v186, v188
	v_permlane16_swap_b32_e32 v187, v189
	v_permlane16_swap_b32_e32 v234, v236
	v_permlane16_swap_b32_e32 v235, v237
	v_lshlrev_b32_e32 v246, 16, v186
	v_and_b32_e32 v247, 0xffff0000, v186
	v_lshlrev_b32_e32 v248, 16, v187
	v_and_b32_e32 v249, 0xffff0000, v187
	v_pk_mul_f32 v[246:247], v[86:87], v[246:247]
	v_pk_mul_f32 v[248:249], v[88:89], v[248:249]
	v_lshlrev_b32_e32 v216, 16, v234
	v_and_b32_e32 v217, 0xffff0000, v234
	v_lshlrev_b32_e32 v220, 16, v235
	v_and_b32_e32 v221, 0xffff0000, v235
	v_pk_add_f32 v[246:247], v[246:247], v[216:217]
	v_pk_add_f32 v[248:249], v[248:249], v[220:221]
	v_cvt_pk_bf16_f32 v186, v246, v247
	v_cvt_pk_bf16_f32 v187, v248, v249
	v_lshlrev_b32_e32 v246, 16, v188
	v_and_b32_e32 v247, 0xffff0000, v188
	v_lshlrev_b32_e32 v248, 16, v189
	v_and_b32_e32 v249, 0xffff0000, v189
	v_pk_mul_f32 v[246:247], v[82:83], v[246:247]
	v_pk_mul_f32 v[248:249], v[84:85], v[248:249]
	v_lshlrev_b32_e32 v216, 16, v236
	v_and_b32_e32 v217, 0xffff0000, v236
	v_lshlrev_b32_e32 v220, 16, v237
	v_and_b32_e32 v221, 0xffff0000, v237
	v_pk_add_f32 v[246:247], v[246:247], v[216:217]
	v_pk_add_f32 v[248:249], v[248:249], v[220:221]
	v_cvt_pk_bf16_f32 v188, v246, v247
	v_cvt_pk_bf16_f32 v189, v248, v249
	s_nop 1
	v_permlane16_swap_b32_e32 v186, v188
	v_permlane16_swap_b32_e32 v187, v189
	global_store_dwordx4 v[160:161], v[186:189], off offset:256
	s_nop 0
	s_mov_b32 s42, 0x90000
	v_lshl_add_u64 v[148:149], v[144:145], 0, s[42:43]
	global_load_dwordx4 v[186:189], v[148:149], off offset:256
	s_mov_b32 s42, 0x48000
	v_lshl_add_u64 v[160:161], v[146:147], 0, s[42:43]
	global_load_dwordx4 v[234:237], v[160:161], off offset:256
	s_waitcnt vmcnt(20)
	v_permlane16_swap_b32_e32 v190, v192
	v_permlane16_swap_b32_e32 v191, v193
	v_permlane16_swap_b32_e32 v238, v240
	v_permlane16_swap_b32_e32 v239, v241
	v_lshlrev_b32_e32 v246, 16, v190
	v_and_b32_e32 v247, 0xffff0000, v190
	v_lshlrev_b32_e32 v248, 16, v191
	v_and_b32_e32 v249, 0xffff0000, v191
	v_pk_mul_f32 v[246:247], v[78:79], v[246:247]
	v_pk_mul_f32 v[248:249], v[80:81], v[248:249]
	v_lshlrev_b32_e32 v216, 16, v238
	v_and_b32_e32 v217, 0xffff0000, v238
	v_lshlrev_b32_e32 v220, 16, v239
	v_and_b32_e32 v221, 0xffff0000, v239
	v_pk_add_f32 v[246:247], v[246:247], v[216:217]
	v_pk_add_f32 v[248:249], v[248:249], v[220:221]
	v_cvt_pk_bf16_f32 v190, v246, v247
	v_cvt_pk_bf16_f32 v191, v248, v249
	v_lshlrev_b32_e32 v246, 16, v192
	v_and_b32_e32 v247, 0xffff0000, v192
	v_lshlrev_b32_e32 v248, 16, v193
	v_and_b32_e32 v249, 0xffff0000, v193
	v_pk_mul_f32 v[246:247], v[74:75], v[246:247]
	v_pk_mul_f32 v[248:249], v[76:77], v[248:249]
	v_lshlrev_b32_e32 v216, 16, v240
	v_and_b32_e32 v217, 0xffff0000, v240
	v_lshlrev_b32_e32 v220, 16, v241
	v_and_b32_e32 v221, 0xffff0000, v241
	v_pk_add_f32 v[246:247], v[246:247], v[216:217]
	v_pk_add_f32 v[248:249], v[248:249], v[220:221]
	v_cvt_pk_bf16_f32 v192, v246, v247
	v_cvt_pk_bf16_f32 v193, v248, v249
	s_nop 1
	v_permlane16_swap_b32_e32 v190, v192
	v_permlane16_swap_b32_e32 v191, v193
	global_store_dwordx4 v[162:163], v[190:193], off offset:256
	s_nop 0
	s_mov_b32 s42, 0xa0000
	v_lshl_add_u64 v[148:149], v[144:145], 0, s[42:43]
	global_load_dwordx4 v[190:193], v[148:149], off offset:256
	s_mov_b32 s42, 0x50000
	v_lshl_add_u64 v[162:163], v[146:147], 0, s[42:43]
	global_load_dwordx4 v[238:241], v[162:163], off offset:256
	s_waitcnt vmcnt(21)
	v_permlane16_swap_b32_e32 v194, v196
	v_permlane16_swap_b32_e32 v195, v197
	v_permlane16_swap_b32_e32 v242, v244
	v_permlane16_swap_b32_e32 v243, v245
	v_lshlrev_b32_e32 v246, 16, v194
	v_and_b32_e32 v247, 0xffff0000, v194
	v_lshlrev_b32_e32 v248, 16, v195
	v_and_b32_e32 v249, 0xffff0000, v195
	v_pk_mul_f32 v[246:247], v[70:71], v[246:247]
	v_pk_mul_f32 v[248:249], v[72:73], v[248:249]
	v_lshlrev_b32_e32 v216, 16, v242
	v_and_b32_e32 v217, 0xffff0000, v242
	v_lshlrev_b32_e32 v220, 16, v243
	v_and_b32_e32 v221, 0xffff0000, v243
	v_pk_add_f32 v[246:247], v[246:247], v[216:217]
	v_pk_add_f32 v[248:249], v[248:249], v[220:221]
	v_cvt_pk_bf16_f32 v194, v246, v247
	v_cvt_pk_bf16_f32 v195, v248, v249
	v_lshlrev_b32_e32 v246, 16, v196
	v_and_b32_e32 v247, 0xffff0000, v196
	v_lshlrev_b32_e32 v248, 16, v197
	v_and_b32_e32 v249, 0xffff0000, v197
	v_pk_mul_f32 v[246:247], v[66:67], v[246:247]
	v_pk_mul_f32 v[248:249], v[68:69], v[248:249]
	v_lshlrev_b32_e32 v216, 16, v244
	v_and_b32_e32 v217, 0xffff0000, v244
	v_lshlrev_b32_e32 v220, 16, v245
	v_and_b32_e32 v221, 0xffff0000, v245
	v_pk_add_f32 v[246:247], v[246:247], v[216:217]
	v_pk_add_f32 v[248:249], v[248:249], v[220:221]
	v_cvt_pk_bf16_f32 v196, v246, v247
	v_cvt_pk_bf16_f32 v197, v248, v249
	s_nop 1
	v_permlane16_swap_b32_e32 v194, v196
	v_permlane16_swap_b32_e32 v195, v197
	global_store_dwordx4 v[164:165], v[194:197], off offset:256
	s_nop 0
	s_mov_b32 s42, 0xb0000
	v_lshl_add_u64 v[148:149], v[144:145], 0, s[42:43]
	global_load_dwordx4 v[194:197], v[148:149], off offset:256
	s_mov_b32 s42, 0x58000
	v_lshl_add_u64 v[164:165], v[146:147], 0, s[42:43]
	global_load_dwordx4 v[242:245], v[164:165], off offset:256
	s_waitcnt vmcnt(21)
	v_permlane16_swap_b32_e32 v166, v168
	v_permlane16_swap_b32_e32 v167, v169
	v_permlane16_swap_b32_e32 v198, v200
	v_permlane16_swap_b32_e32 v199, v201
	v_lshlrev_b32_e32 v246, 16, v166
	v_and_b32_e32 v247, 0xffff0000, v166
	v_lshlrev_b32_e32 v248, 16, v167
	v_and_b32_e32 v249, 0xffff0000, v167
	v_pk_mul_f32 v[246:247], v[62:63], v[246:247]
	v_pk_mul_f32 v[248:249], v[64:65], v[248:249]
	v_lshlrev_b32_e32 v216, 16, v198
	v_and_b32_e32 v217, 0xffff0000, v198
	v_lshlrev_b32_e32 v220, 16, v199
	v_and_b32_e32 v221, 0xffff0000, v199
	v_pk_add_f32 v[246:247], v[246:247], v[216:217]
	v_pk_add_f32 v[248:249], v[248:249], v[220:221]
	v_cvt_pk_bf16_f32 v166, v246, v247
	v_cvt_pk_bf16_f32 v167, v248, v249
	v_lshlrev_b32_e32 v246, 16, v168
	v_and_b32_e32 v247, 0xffff0000, v168
	v_lshlrev_b32_e32 v248, 16, v169
	v_and_b32_e32 v249, 0xffff0000, v169
	v_pk_mul_f32 v[246:247], v[58:59], v[246:247]
	v_pk_mul_f32 v[248:249], v[60:61], v[248:249]
	v_lshlrev_b32_e32 v216, 16, v200
	v_and_b32_e32 v217, 0xffff0000, v200
	v_lshlrev_b32_e32 v220, 16, v201
	v_and_b32_e32 v221, 0xffff0000, v201
	v_pk_add_f32 v[246:247], v[246:247], v[216:217]
	v_pk_add_f32 v[248:249], v[248:249], v[220:221]
	v_cvt_pk_bf16_f32 v168, v246, v247
	v_cvt_pk_bf16_f32 v169, v248, v249
	s_nop 1
	v_permlane16_swap_b32_e32 v166, v168
	v_permlane16_swap_b32_e32 v167, v169
	global_store_dwordx4 v[150:151], v[166:169], off offset:0
	s_waitcnt vmcnt(19)
	v_permlane16_swap_b32_e32 v170, v172
	v_permlane16_swap_b32_e32 v171, v173
	v_permlane16_swap_b32_e32 v202, v204
	v_permlane16_swap_b32_e32 v203, v205
	v_lshlrev_b32_e32 v246, 16, v170
	v_and_b32_e32 v247, 0xffff0000, v170
	v_lshlrev_b32_e32 v248, 16, v171
	v_and_b32_e32 v249, 0xffff0000, v171
	v_pk_mul_f32 v[246:247], v[54:55], v[246:247]
	v_pk_mul_f32 v[248:249], v[56:57], v[248:249]
	v_lshlrev_b32_e32 v216, 16, v202
	v_and_b32_e32 v217, 0xffff0000, v202
	v_lshlrev_b32_e32 v220, 16, v203
	v_and_b32_e32 v221, 0xffff0000, v203
	v_pk_add_f32 v[246:247], v[246:247], v[216:217]
	v_pk_add_f32 v[248:249], v[248:249], v[220:221]
	v_cvt_pk_bf16_f32 v170, v246, v247
	v_cvt_pk_bf16_f32 v171, v248, v249
	v_lshlrev_b32_e32 v246, 16, v172
	v_and_b32_e32 v247, 0xffff0000, v172
	v_lshlrev_b32_e32 v248, 16, v173
	v_and_b32_e32 v249, 0xffff0000, v173
	v_pk_mul_f32 v[246:247], v[50:51], v[246:247]
	v_pk_mul_f32 v[248:249], v[52:53], v[248:249]
	v_lshlrev_b32_e32 v216, 16, v204
	v_and_b32_e32 v217, 0xffff0000, v204
	v_lshlrev_b32_e32 v220, 16, v205
	v_and_b32_e32 v221, 0xffff0000, v205
	v_pk_add_f32 v[246:247], v[246:247], v[216:217]
	v_pk_add_f32 v[248:249], v[248:249], v[220:221]
	v_cvt_pk_bf16_f32 v172, v246, v247
	v_cvt_pk_bf16_f32 v173, v248, v249
	s_nop 1
	v_permlane16_swap_b32_e32 v170, v172
	v_permlane16_swap_b32_e32 v171, v173
	global_store_dwordx4 v[152:153], v[170:173], off offset:0
	s_waitcnt vmcnt(17)
	v_permlane16_swap_b32_e32 v174, v176
	v_permlane16_swap_b32_e32 v175, v177
	v_permlane16_swap_b32_e32 v206, v208
	v_permlane16_swap_b32_e32 v207, v209
	v_lshlrev_b32_e32 v246, 16, v174
	v_and_b32_e32 v247, 0xffff0000, v174
	v_lshlrev_b32_e32 v248, 16, v175
	v_and_b32_e32 v249, 0xffff0000, v175
	v_pk_mul_f32 v[246:247], v[46:47], v[246:247]
	v_pk_mul_f32 v[248:249], v[48:49], v[248:249]
	v_lshlrev_b32_e32 v216, 16, v206
	v_and_b32_e32 v217, 0xffff0000, v206
	v_lshlrev_b32_e32 v220, 16, v207
	v_and_b32_e32 v221, 0xffff0000, v207
	v_pk_add_f32 v[246:247], v[246:247], v[216:217]
	v_pk_add_f32 v[248:249], v[248:249], v[220:221]
	v_cvt_pk_bf16_f32 v174, v246, v247
	v_cvt_pk_bf16_f32 v175, v248, v249
	v_lshlrev_b32_e32 v246, 16, v176
	v_and_b32_e32 v247, 0xffff0000, v176
	v_lshlrev_b32_e32 v248, 16, v177
	v_and_b32_e32 v249, 0xffff0000, v177
	v_pk_mul_f32 v[246:247], v[42:43], v[246:247]
	v_pk_mul_f32 v[248:249], v[44:45], v[248:249]
	v_lshlrev_b32_e32 v216, 16, v208
	v_and_b32_e32 v217, 0xffff0000, v208
	v_lshlrev_b32_e32 v220, 16, v209
	v_and_b32_e32 v221, 0xffff0000, v209
	v_pk_add_f32 v[246:247], v[246:247], v[216:217]
	v_pk_add_f32 v[248:249], v[248:249], v[220:221]
	v_cvt_pk_bf16_f32 v176, v246, v247
	v_cvt_pk_bf16_f32 v177, v248, v249
	s_nop 1
	v_permlane16_swap_b32_e32 v174, v176
	v_permlane16_swap_b32_e32 v175, v177
	global_store_dwordx4 v[154:155], v[174:177], off offset:0
	s_waitcnt vmcnt(15)
	v_permlane16_swap_b32_e32 v178, v180
	v_permlane16_swap_b32_e32 v179, v181
	v_permlane16_swap_b32_e32 v226, v228
	v_permlane16_swap_b32_e32 v227, v229
	v_lshlrev_b32_e32 v246, 16, v178
	v_and_b32_e32 v247, 0xffff0000, v178
	v_lshlrev_b32_e32 v248, 16, v179
	v_and_b32_e32 v249, 0xffff0000, v179
	v_pk_mul_f32 v[246:247], v[38:39], v[246:247]
	v_pk_mul_f32 v[248:249], v[40:41], v[248:249]
	v_lshlrev_b32_e32 v216, 16, v226
	v_and_b32_e32 v217, 0xffff0000, v226
	v_lshlrev_b32_e32 v220, 16, v227
	v_and_b32_e32 v221, 0xffff0000, v227
	v_pk_add_f32 v[246:247], v[246:247], v[216:217]
	v_pk_add_f32 v[248:249], v[248:249], v[220:221]
	v_cvt_pk_bf16_f32 v178, v246, v247
	v_cvt_pk_bf16_f32 v179, v248, v249
	v_lshlrev_b32_e32 v246, 16, v180
	v_and_b32_e32 v247, 0xffff0000, v180
	v_lshlrev_b32_e32 v248, 16, v181
	v_and_b32_e32 v249, 0xffff0000, v181
	v_pk_mul_f32 v[246:247], v[34:35], v[246:247]
	v_pk_mul_f32 v[248:249], v[36:37], v[248:249]
	v_lshlrev_b32_e32 v216, 16, v228
	v_and_b32_e32 v217, 0xffff0000, v228
	v_lshlrev_b32_e32 v220, 16, v229
	v_and_b32_e32 v221, 0xffff0000, v229
	v_pk_add_f32 v[246:247], v[246:247], v[216:217]
	v_pk_add_f32 v[248:249], v[248:249], v[220:221]
	v_cvt_pk_bf16_f32 v180, v246, v247
	v_cvt_pk_bf16_f32 v181, v248, v249
	s_nop 1
	v_permlane16_swap_b32_e32 v178, v180
	v_permlane16_swap_b32_e32 v179, v181
	global_store_dwordx4 v[156:157], v[178:181], off offset:0
	s_waitcnt vmcnt(13)
	v_permlane16_swap_b32_e32 v182, v184
	v_permlane16_swap_b32_e32 v183, v185
	v_permlane16_swap_b32_e32 v230, v232
	v_permlane16_swap_b32_e32 v231, v233
	v_lshlrev_b32_e32 v246, 16, v182
	v_and_b32_e32 v247, 0xffff0000, v182
	v_lshlrev_b32_e32 v248, 16, v183
	v_and_b32_e32 v249, 0xffff0000, v183
	v_pk_mul_f32 v[246:247], v[30:31], v[246:247]
	v_pk_mul_f32 v[248:249], v[32:33], v[248:249]
	v_lshlrev_b32_e32 v216, 16, v230
	v_and_b32_e32 v217, 0xffff0000, v230
	v_lshlrev_b32_e32 v220, 16, v231
	v_and_b32_e32 v221, 0xffff0000, v231
	v_pk_add_f32 v[246:247], v[246:247], v[216:217]
	v_pk_add_f32 v[248:249], v[248:249], v[220:221]
	v_cvt_pk_bf16_f32 v182, v246, v247
	v_cvt_pk_bf16_f32 v183, v248, v249
	v_lshlrev_b32_e32 v246, 16, v184
	v_and_b32_e32 v247, 0xffff0000, v184
	v_lshlrev_b32_e32 v248, 16, v185
	v_and_b32_e32 v249, 0xffff0000, v185
	v_pk_mul_f32 v[246:247], v[26:27], v[246:247]
	v_pk_mul_f32 v[248:249], v[28:29], v[248:249]
	v_lshlrev_b32_e32 v216, 16, v232
	v_and_b32_e32 v217, 0xffff0000, v232
	v_lshlrev_b32_e32 v220, 16, v233
	v_and_b32_e32 v221, 0xffff0000, v233
	v_pk_add_f32 v[246:247], v[246:247], v[216:217]
	v_pk_add_f32 v[248:249], v[248:249], v[220:221]
	v_cvt_pk_bf16_f32 v184, v246, v247
	v_cvt_pk_bf16_f32 v185, v248, v249
	s_nop 1
	v_permlane16_swap_b32_e32 v182, v184
	v_permlane16_swap_b32_e32 v183, v185
	global_store_dwordx4 v[158:159], v[182:185], off offset:256
	s_waitcnt vmcnt(11)
	v_permlane16_swap_b32_e32 v186, v188
	v_permlane16_swap_b32_e32 v187, v189
	v_permlane16_swap_b32_e32 v234, v236
	v_permlane16_swap_b32_e32 v235, v237
	v_lshlrev_b32_e32 v246, 16, v186
	v_and_b32_e32 v247, 0xffff0000, v186
	v_lshlrev_b32_e32 v248, 16, v187
	v_and_b32_e32 v249, 0xffff0000, v187
	v_pk_mul_f32 v[246:247], v[22:23], v[246:247]
	v_pk_mul_f32 v[248:249], v[24:25], v[248:249]
	v_lshlrev_b32_e32 v216, 16, v234
	v_and_b32_e32 v217, 0xffff0000, v234
	v_lshlrev_b32_e32 v220, 16, v235
	v_and_b32_e32 v221, 0xffff0000, v235
	v_pk_add_f32 v[246:247], v[246:247], v[216:217]
	v_pk_add_f32 v[248:249], v[248:249], v[220:221]
	v_cvt_pk_bf16_f32 v186, v246, v247
	v_cvt_pk_bf16_f32 v187, v248, v249
	v_lshlrev_b32_e32 v246, 16, v188
	v_and_b32_e32 v247, 0xffff0000, v188
	v_lshlrev_b32_e32 v248, 16, v189
	v_and_b32_e32 v249, 0xffff0000, v189
	v_pk_mul_f32 v[246:247], v[18:19], v[246:247]
	v_pk_mul_f32 v[248:249], v[20:21], v[248:249]
	v_lshlrev_b32_e32 v216, 16, v236
	v_and_b32_e32 v217, 0xffff0000, v236
	v_lshlrev_b32_e32 v220, 16, v237
	v_and_b32_e32 v221, 0xffff0000, v237
	v_pk_add_f32 v[246:247], v[246:247], v[216:217]
	v_pk_add_f32 v[248:249], v[248:249], v[220:221]
	v_cvt_pk_bf16_f32 v188, v246, v247
	v_cvt_pk_bf16_f32 v189, v248, v249
	s_nop 1
	v_permlane16_swap_b32_e32 v186, v188
	v_permlane16_swap_b32_e32 v187, v189
	global_store_dwordx4 v[160:161], v[186:189], off offset:256
	s_waitcnt vmcnt(9)
	v_permlane16_swap_b32_e32 v190, v192
	v_permlane16_swap_b32_e32 v191, v193
	v_permlane16_swap_b32_e32 v238, v240
	v_permlane16_swap_b32_e32 v239, v241
	v_lshlrev_b32_e32 v246, 16, v190
	v_and_b32_e32 v247, 0xffff0000, v190
	v_lshlrev_b32_e32 v248, 16, v191
	v_and_b32_e32 v249, 0xffff0000, v191
	v_pk_mul_f32 v[246:247], v[14:15], v[246:247]
	v_pk_mul_f32 v[248:249], v[16:17], v[248:249]
	v_lshlrev_b32_e32 v216, 16, v238
	v_and_b32_e32 v217, 0xffff0000, v238
	v_lshlrev_b32_e32 v220, 16, v239
	v_and_b32_e32 v221, 0xffff0000, v239
	v_pk_add_f32 v[246:247], v[246:247], v[216:217]
	v_pk_add_f32 v[248:249], v[248:249], v[220:221]
	v_cvt_pk_bf16_f32 v190, v246, v247
	v_cvt_pk_bf16_f32 v191, v248, v249
	v_lshlrev_b32_e32 v246, 16, v192
	v_and_b32_e32 v247, 0xffff0000, v192
	v_lshlrev_b32_e32 v248, 16, v193
	v_and_b32_e32 v249, 0xffff0000, v193
	v_pk_mul_f32 v[246:247], v[10:11], v[246:247]
	v_pk_mul_f32 v[248:249], v[12:13], v[248:249]
	v_lshlrev_b32_e32 v216, 16, v240
	v_and_b32_e32 v217, 0xffff0000, v240
	v_lshlrev_b32_e32 v220, 16, v241
	v_and_b32_e32 v221, 0xffff0000, v241
	v_pk_add_f32 v[246:247], v[246:247], v[216:217]
	v_pk_add_f32 v[248:249], v[248:249], v[220:221]
	v_cvt_pk_bf16_f32 v192, v246, v247
	v_cvt_pk_bf16_f32 v193, v248, v249
	s_nop 1
	v_permlane16_swap_b32_e32 v190, v192
	v_permlane16_swap_b32_e32 v191, v193
	global_store_dwordx4 v[162:163], v[190:193], off offset:256
	s_waitcnt vmcnt(7)
	v_permlane16_swap_b32_e32 v194, v196
	v_permlane16_swap_b32_e32 v195, v197
	v_permlane16_swap_b32_e32 v242, v244
	v_permlane16_swap_b32_e32 v243, v245
	v_lshlrev_b32_e32 v246, 16, v194
	v_and_b32_e32 v247, 0xffff0000, v194
	v_lshlrev_b32_e32 v248, 16, v195
	v_and_b32_e32 v249, 0xffff0000, v195
	v_pk_mul_f32 v[246:247], v[6:7], v[246:247]
	v_pk_mul_f32 v[248:249], v[8:9], v[248:249]
	v_lshlrev_b32_e32 v216, 16, v242
	v_and_b32_e32 v217, 0xffff0000, v242
	v_lshlrev_b32_e32 v220, 16, v243
	v_and_b32_e32 v221, 0xffff0000, v243
	v_pk_add_f32 v[246:247], v[246:247], v[216:217]
	v_pk_add_f32 v[248:249], v[248:249], v[220:221]
	v_cvt_pk_bf16_f32 v194, v246, v247
	v_cvt_pk_bf16_f32 v195, v248, v249
	v_lshlrev_b32_e32 v246, 16, v196
	v_and_b32_e32 v247, 0xffff0000, v196
	v_lshlrev_b32_e32 v248, 16, v197
	v_and_b32_e32 v249, 0xffff0000, v197
	v_pk_mul_f32 v[246:247], v[2:3], v[246:247]
	v_pk_mul_f32 v[248:249], v[4:5], v[248:249]
	v_lshlrev_b32_e32 v216, 16, v244
	v_and_b32_e32 v217, 0xffff0000, v244
	v_lshlrev_b32_e32 v220, 16, v245
	v_and_b32_e32 v221, 0xffff0000, v245
	v_pk_add_f32 v[246:247], v[246:247], v[216:217]
	v_pk_add_f32 v[248:249], v[248:249], v[220:221]
	v_cvt_pk_bf16_f32 v196, v246, v247
	v_cvt_pk_bf16_f32 v197, v248, v249
	s_nop 1
	v_permlane16_swap_b32_e32 v194, v196
	v_permlane16_swap_b32_e32 v195, v197
	global_store_dwordx4 v[164:165], v[194:197], off offset:256
	s_branch .Lmix_done
.Lmix_pass0c:
	s_mov_b32 s42, 0x0
	v_lshl_add_u64 v[148:149], v[144:145], 0, s[42:43]
	global_load_dwordx4 v[166:169], v[148:149], off offset:0
	s_mov_b32 s42, 0x0
	v_lshl_add_u64 v[150:151], v[146:147], 0, s[42:43]
	s_mov_b32 s42, 0x10000
	v_lshl_add_u64 v[148:149], v[144:145], 0, s[42:43]
	global_load_dwordx4 v[170:173], v[148:149], off offset:0
	s_mov_b32 s42, 0x8000
	v_lshl_add_u64 v[152:153], v[146:147], 0, s[42:43]
	s_mov_b32 s42, 0x20000
	v_lshl_add_u64 v[148:149], v[144:145], 0, s[42:43]
	global_load_dwordx4 v[174:177], v[148:149], off offset:0
	s_mov_b32 s42, 0x10000
	v_lshl_add_u64 v[154:155], v[146:147], 0, s[42:43]
	s_mov_b32 s42, 0x30000
	v_lshl_add_u64 v[148:149], v[144:145], 0, s[42:43]
	global_load_dwordx4 v[178:181], v[148:149], off offset:0
	s_mov_b32 s42, 0x18000
	v_lshl_add_u64 v[156:157], v[146:147], 0, s[42:43]
	s_mov_b32 s42, 0x0
	v_lshl_add_u64 v[148:149], v[144:145], 0, s[42:43]
	global_load_dwordx4 v[182:185], v[148:149], off offset:256
	s_mov_b32 s42, 0x0
	v_lshl_add_u64 v[158:159], v[146:147], 0, s[42:43]
	s_mov_b32 s42, 0x10000
	v_lshl_add_u64 v[148:149], v[144:145], 0, s[42:43]
	global_load_dwordx4 v[186:189], v[148:149], off offset:256
	s_mov_b32 s42, 0x8000
	v_lshl_add_u64 v[160:161], v[146:147], 0, s[42:43]
	s_mov_b32 s42, 0x20000
	v_lshl_add_u64 v[148:149], v[144:145], 0, s[42:43]
	global_load_dwordx4 v[190:193], v[148:149], off offset:256
	s_mov_b32 s42, 0x10000
	v_lshl_add_u64 v[162:163], v[146:147], 0, s[42:43]
	s_mov_b32 s42, 0x30000
	v_lshl_add_u64 v[148:149], v[144:145], 0, s[42:43]
	global_load_dwordx4 v[194:197], v[148:149], off offset:256
	s_mov_b32 s42, 0x18000
	v_lshl_add_u64 v[164:165], v[146:147], 0, s[42:43]
	s_waitcnt vmcnt(7)
	v_permlane16_swap_b32_e32 v166, v168
	v_permlane16_swap_b32_e32 v167, v169
	v_lshlrev_b32_e32 v246, 16, v166
	v_and_b32_e32 v247, 0xffff0000, v166
	v_lshlrev_b32_e32 v248, 16, v167
	v_and_b32_e32 v249, 0xffff0000, v167
	v_pk_mul_f32 v[246:247], v[126:127], v[246:247]
	v_pk_mul_f32 v[248:249], v[128:129], v[248:249]
	v_cvt_pk_bf16_f32 v166, v246, v247
	v_cvt_pk_bf16_f32 v167, v248, v249
	v_lshlrev_b32_e32 v246, 16, v168
	v_and_b32_e32 v247, 0xffff0000, v168
	v_lshlrev_b32_e32 v248, 16, v169
	v_and_b32_e32 v249, 0xffff0000, v169
	v_pk_mul_f32 v[246:247], v[122:123], v[246:247]
	v_pk_mul_f32 v[248:249], v[124:125], v[248:249]
	v_cvt_pk_bf16_f32 v168, v246, v247
	v_cvt_pk_bf16_f32 v169, v248, v249
	s_nop 1
	v_permlane16_swap_b32_e32 v166, v168
	v_permlane16_swap_b32_e32 v167, v169
	global_store_dwordx4 v[150:151], v[166:169], off offset:0 sc1
	s_nop 0
	s_mov_b32 s42, 0x80000
	v_lshl_add_u64 v[148:149], v[144:145], 0, s[42:43]
	global_load_dwordx4 v[166:169], v[148:149], off offset:0
	s_mov_b32 s42, 0x40000
	v_lshl_add_u64 v[150:151], v[146:147], 0, s[42:43]
	s_waitcnt vmcnt(8)
	v_permlane16_swap_b32_e32 v170, v172
	v_permlane16_swap_b32_e32 v171, v173
	v_lshlrev_b32_e32 v246, 16, v170
	v_and_b32_e32 v247, 0xffff0000, v170
	v_lshlrev_b32_e32 v248, 16, v171
	v_and_b32_e32 v249, 0xffff0000, v171
	v_pk_mul_f32 v[246:247], v[118:119], v[246:247]
	v_pk_mul_f32 v[248:249], v[120:121], v[248:249]
	v_cvt_pk_bf16_f32 v170, v246, v247
	v_cvt_pk_bf16_f32 v171, v248, v249
	v_lshlrev_b32_e32 v246, 16, v172
	v_and_b32_e32 v247, 0xffff0000, v172
	v_lshlrev_b32_e32 v248, 16, v173
	v_and_b32_e32 v249, 0xffff0000, v173
	v_pk_mul_f32 v[246:247], v[114:115], v[246:247]
	v_pk_mul_f32 v[248:249], v[116:117], v[248:249]
	v_cvt_pk_bf16_f32 v172, v246, v247
	v_cvt_pk_bf16_f32 v173, v248, v249
	s_nop 1
	v_permlane16_swap_b32_e32 v170, v172
	v_permlane16_swap_b32_e32 v171, v173
	global_store_dwordx4 v[152:153], v[170:173], off offset:0 sc1
	s_nop 0
	s_mov_b32 s42, 0x90000
	v_lshl_add_u64 v[148:149], v[144:145], 0, s[42:43]
	global_load_dwordx4 v[170:173], v[148:149], off offset:0
	s_mov_b32 s42, 0x48000
	v_lshl_add_u64 v[152:153], v[146:147], 0, s[42:43]
	s_waitcnt vmcnt(9)
	v_permlane16_swap_b32_e32 v174, v176
	v_permlane16_swap_b32_e32 v175, v177
	v_lshlrev_b32_e32 v246, 16, v174
	v_and_b32_e32 v247, 0xffff0000, v174
	v_lshlrev_b32_e32 v248, 16, v175
	v_and_b32_e32 v249, 0xffff0000, v175
	v_pk_mul_f32 v[246:247], v[110:111], v[246:247]
	v_pk_mul_f32 v[248:249], v[112:113], v[248:249]
	v_cvt_pk_bf16_f32 v174, v246, v247
	v_cvt_pk_bf16_f32 v175, v248, v249
	v_lshlrev_b32_e32 v246, 16, v176
	v_and_b32_e32 v247, 0xffff0000, v176
	v_lshlrev_b32_e32 v248, 16, v177
	v_and_b32_e32 v249, 0xffff0000, v177
	v_pk_mul_f32 v[246:247], v[106:107], v[246:247]
	v_pk_mul_f32 v[248:249], v[108:109], v[248:249]
	v_cvt_pk_bf16_f32 v176, v246, v247
	v_cvt_pk_bf16_f32 v177, v248, v249
	s_nop 1
	v_permlane16_swap_b32_e32 v174, v176
	v_permlane16_swap_b32_e32 v175, v177
	global_store_dwordx4 v[154:155], v[174:177], off offset:0 sc1
	s_nop 0
	s_mov_b32 s42, 0xa0000
	v_lshl_add_u64 v[148:149], v[144:145], 0, s[42:43]
	global_load_dwordx4 v[174:177], v[148:149], off offset:0
	s_mov_b32 s42, 0x50000
	v_lshl_add_u64 v[154:155], v[146:147], 0, s[42:43]
	s_waitcnt vmcnt(10)
	v_permlane16_swap_b32_e32 v178, v180
	v_permlane16_swap_b32_e32 v179, v181
	v_lshlrev_b32_e32 v246, 16, v178
	v_and_b32_e32 v247, 0xffff0000, v178
	v_lshlrev_b32_e32 v248, 16, v179
	v_and_b32_e32 v249, 0xffff0000, v179
	v_pk_mul_f32 v[246:247], v[102:103], v[246:247]
	v_pk_mul_f32 v[248:249], v[104:105], v[248:249]
	v_cvt_pk_bf16_f32 v178, v246, v247
	v_cvt_pk_bf16_f32 v179, v248, v249
	v_lshlrev_b32_e32 v246, 16, v180
	v_and_b32_e32 v247, 0xffff0000, v180
	v_lshlrev_b32_e32 v248, 16, v181
	v_and_b32_e32 v249, 0xffff0000, v181
	v_pk_mul_f32 v[246:247], v[98:99], v[246:247]
	v_pk_mul_f32 v[248:249], v[100:101], v[248:249]
	v_cvt_pk_bf16_f32 v180, v246, v247
	v_cvt_pk_bf16_f32 v181, v248, v249
	s_nop 1
	v_permlane16_swap_b32_e32 v178, v180
	v_permlane16_swap_b32_e32 v179, v181
	global_store_dwordx4 v[156:157], v[178:181], off offset:0 sc1
	s_nop 0
	s_mov_b32 s42, 0xb0000
	v_lshl_add_u64 v[148:149], v[144:145], 0, s[42:43]
	global_load_dwordx4 v[178:181], v[148:149], off offset:0
	s_mov_b32 s42, 0x58000
	v_lshl_add_u64 v[156:157], v[146:147], 0, s[42:43]
	s_waitcnt vmcnt(11)
	v_permlane16_swap_b32_e32 v182, v184
	v_permlane16_swap_b32_e32 v183, v185
	v_lshlrev_b32_e32 v246, 16, v182
	v_and_b32_e32 v247, 0xffff0000, v182
	v_lshlrev_b32_e32 v248, 16, v183
	v_and_b32_e32 v249, 0xffff0000, v183
	v_pk_mul_f32 v[246:247], v[94:95], v[246:247]
	v_pk_mul_f32 v[248:249], v[96:97], v[248:249]
	v_cvt_pk_bf16_f32 v182, v246, v247
	v_cvt_pk_bf16_f32 v183, v248, v249
	v_lshlrev_b32_e32 v246, 16, v184
	v_and_b32_e32 v247, 0xffff0000, v184
	v_lshlrev_b32_e32 v248, 16, v185
	v_and_b32_e32 v249, 0xffff0000, v185
	v_pk_mul_f32 v[246:247], v[90:91], v[246:247]
	v_pk_mul_f32 v[248:249], v[92:93], v[248:249]
	v_cvt_pk_bf16_f32 v184, v246, v247
	v_cvt_pk_bf16_f32 v185, v248, v249
	s_nop 1
	v_permlane16_swap_b32_e32 v182, v184
	v_permlane16_swap_b32_e32 v183, v185
	global_store_dwordx4 v[158:159], v[182:185], off offset:256 sc1
	s_nop 0
	s_mov_b32 s42, 0x80000
	v_lshl_add_u64 v[148:149], v[144:145], 0, s[42:43]
	global_load_dwordx4 v[182:185], v[148:149], off offset:256
	s_mov_b32 s42, 0x40000
	v_lshl_add_u64 v[158:159], v[146:147], 0, s[42:43]
	s_waitcnt vmcnt(12)
	v_permlane16_swap_b32_e32 v186, v188
	v_permlane16_swap_b32_e32 v187, v189
	v_lshlrev_b32_e32 v246, 16, v186
	v_and_b32_e32 v247, 0xffff0000, v186
	v_lshlrev_b32_e32 v248, 16, v187
	v_and_b32_e32 v249, 0xffff0000, v187
	v_pk_mul_f32 v[246:247], v[86:87], v[246:247]
	v_pk_mul_f32 v[248:249], v[88:89], v[248:249]
	v_cvt_pk_bf16_f32 v186, v246, v247
	v_cvt_pk_bf16_f32 v187, v248, v249
	v_lshlrev_b32_e32 v246, 16, v188
	v_and_b32_e32 v247, 0xffff0000, v188
	v_lshlrev_b32_e32 v248, 16, v189
	v_and_b32_e32 v249, 0xffff0000, v189
	v_pk_mul_f32 v[246:247], v[82:83], v[246:247]
	v_pk_mul_f32 v[248:249], v[84:85], v[248:249]
	v_cvt_pk_bf16_f32 v188, v246, v247
	v_cvt_pk_bf16_f32 v189, v248, v249
	s_nop 1
	v_permlane16_swap_b32_e32 v186, v188
	v_permlane16_swap_b32_e32 v187, v189
	global_store_dwordx4 v[160:161], v[186:189], off offset:256 sc1
	s_nop 0
	s_mov_b32 s42, 0x90000
	v_lshl_add_u64 v[148:149], v[144:145], 0, s[42:43]
	global_load_dwordx4 v[186:189], v[148:149], off offset:256
	s_mov_b32 s42, 0x48000
	v_lshl_add_u64 v[160:161], v[146:147], 0, s[42:43]
	s_waitcnt vmcnt(13)
	v_permlane16_swap_b32_e32 v190, v192
	v_permlane16_swap_b32_e32 v191, v193
	v_lshlrev_b32_e32 v246, 16, v190
	v_and_b32_e32 v247, 0xffff0000, v190
	v_lshlrev_b32_e32 v248, 16, v191
	v_and_b32_e32 v249, 0xffff0000, v191
	v_pk_mul_f32 v[246:247], v[78:79], v[246:247]
	v_pk_mul_f32 v[248:249], v[80:81], v[248:249]
	v_cvt_pk_bf16_f32 v190, v246, v247
	v_cvt_pk_bf16_f32 v191, v248, v249
	v_lshlrev_b32_e32 v246, 16, v192
	v_and_b32_e32 v247, 0xffff0000, v192
	v_lshlrev_b32_e32 v248, 16, v193
	v_and_b32_e32 v249, 0xffff0000, v193
	v_pk_mul_f32 v[246:247], v[74:75], v[246:247]
	v_pk_mul_f32 v[248:249], v[76:77], v[248:249]
	v_cvt_pk_bf16_f32 v192, v246, v247
	v_cvt_pk_bf16_f32 v193, v248, v249
	s_nop 1
	v_permlane16_swap_b32_e32 v190, v192
	v_permlane16_swap_b32_e32 v191, v193
	global_store_dwordx4 v[162:163], v[190:193], off offset:256 sc1
	s_nop 0
	s_mov_b32 s42, 0xa0000
	v_lshl_add_u64 v[148:149], v[144:145], 0, s[42:43]
	global_load_dwordx4 v[190:193], v[148:149], off offset:256
	s_mov_b32 s42, 0x50000
	v_lshl_add_u64 v[162:163], v[146:147], 0, s[42:43]
	s_waitcnt vmcnt(14)
	v_permlane16_swap_b32_e32 v194, v196
	v_permlane16_swap_b32_e32 v195, v197
	v_lshlrev_b32_e32 v246, 16, v194
	v_and_b32_e32 v247, 0xffff0000, v194
	v_lshlrev_b32_e32 v248, 16, v195
	v_and_b32_e32 v249, 0xffff0000, v195
	v_pk_mul_f32 v[246:247], v[70:71], v[246:247]
	v_pk_mul_f32 v[248:249], v[72:73], v[248:249]
	v_cvt_pk_bf16_f32 v194, v246, v247
	v_cvt_pk_bf16_f32 v195, v248, v249
	v_lshlrev_b32_e32 v246, 16, v196
	v_and_b32_e32 v247, 0xffff0000, v196
	v_lshlrev_b32_e32 v248, 16, v197
	v_and_b32_e32 v249, 0xffff0000, v197
	v_pk_mul_f32 v[246:247], v[66:67], v[246:247]
	v_pk_mul_f32 v[248:249], v[68:69], v[248:249]
	v_cvt_pk_bf16_f32 v196, v246, v247
	v_cvt_pk_bf16_f32 v197, v248, v249
	s_nop 1
	v_permlane16_swap_b32_e32 v194, v196
	v_permlane16_swap_b32_e32 v195, v197
	global_store_dwordx4 v[164:165], v[194:197], off offset:256 sc1
	s_nop 0
	s_mov_b32 s42, 0xb0000
	v_lshl_add_u64 v[148:149], v[144:145], 0, s[42:43]
	global_load_dwordx4 v[194:197], v[148:149], off offset:256
	s_mov_b32 s42, 0x58000
	v_lshl_add_u64 v[164:165], v[146:147], 0, s[42:43]
	s_waitcnt vmcnt(14)
	v_permlane16_swap_b32_e32 v166, v168
	v_permlane16_swap_b32_e32 v167, v169
	v_lshlrev_b32_e32 v246, 16, v166
	v_and_b32_e32 v247, 0xffff0000, v166
	v_lshlrev_b32_e32 v248, 16, v167
	v_and_b32_e32 v249, 0xffff0000, v167
	v_pk_mul_f32 v[246:247], v[62:63], v[246:247]
	v_pk_mul_f32 v[248:249], v[64:65], v[248:249]
	v_cvt_pk_bf16_f32 v166, v246, v247
	v_cvt_pk_bf16_f32 v167, v248, v249
	v_lshlrev_b32_e32 v246, 16, v168
	v_and_b32_e32 v247, 0xffff0000, v168
	v_lshlrev_b32_e32 v248, 16, v169
	v_and_b32_e32 v249, 0xffff0000, v169
	v_pk_mul_f32 v[246:247], v[58:59], v[246:247]
	v_pk_mul_f32 v[248:249], v[60:61], v[248:249]
	v_cvt_pk_bf16_f32 v168, v246, v247
	v_cvt_pk_bf16_f32 v169, v248, v249
	s_nop 1
	v_permlane16_swap_b32_e32 v166, v168
	v_permlane16_swap_b32_e32 v167, v169
	global_store_dwordx4 v[150:151], v[166:169], off offset:0 sc1
	s_waitcnt vmcnt(13)
	v_permlane16_swap_b32_e32 v170, v172
	v_permlane16_swap_b32_e32 v171, v173
	v_lshlrev_b32_e32 v246, 16, v170
	v_and_b32_e32 v247, 0xffff0000, v170
	v_lshlrev_b32_e32 v248, 16, v171
	v_and_b32_e32 v249, 0xffff0000, v171
	v_pk_mul_f32 v[246:247], v[54:55], v[246:247]
	v_pk_mul_f32 v[248:249], v[56:57], v[248:249]
	v_cvt_pk_bf16_f32 v170, v246, v247
	v_cvt_pk_bf16_f32 v171, v248, v249
	v_lshlrev_b32_e32 v246, 16, v172
	v_and_b32_e32 v247, 0xffff0000, v172
	v_lshlrev_b32_e32 v248, 16, v173
	v_and_b32_e32 v249, 0xffff0000, v173
	v_pk_mul_f32 v[246:247], v[50:51], v[246:247]
	v_pk_mul_f32 v[248:249], v[52:53], v[248:249]
	v_cvt_pk_bf16_f32 v172, v246, v247
	v_cvt_pk_bf16_f32 v173, v248, v249
	s_nop 1
	v_permlane16_swap_b32_e32 v170, v172
	v_permlane16_swap_b32_e32 v171, v173
	global_store_dwordx4 v[152:153], v[170:173], off offset:0 sc1
	s_waitcnt vmcnt(12)
	v_permlane16_swap_b32_e32 v174, v176
	v_permlane16_swap_b32_e32 v175, v177
	v_lshlrev_b32_e32 v246, 16, v174
	v_and_b32_e32 v247, 0xffff0000, v174
	v_lshlrev_b32_e32 v248, 16, v175
	v_and_b32_e32 v249, 0xffff0000, v175
	v_pk_mul_f32 v[246:247], v[46:47], v[246:247]
	v_pk_mul_f32 v[248:249], v[48:49], v[248:249]
	v_cvt_pk_bf16_f32 v174, v246, v247
	v_cvt_pk_bf16_f32 v175, v248, v249
	v_lshlrev_b32_e32 v246, 16, v176
	v_and_b32_e32 v247, 0xffff0000, v176
	v_lshlrev_b32_e32 v248, 16, v177
	v_and_b32_e32 v249, 0xffff0000, v177
	v_pk_mul_f32 v[246:247], v[42:43], v[246:247]
	v_pk_mul_f32 v[248:249], v[44:45], v[248:249]
	v_cvt_pk_bf16_f32 v176, v246, v247
	v_cvt_pk_bf16_f32 v177, v248, v249
	s_nop 1
	v_permlane16_swap_b32_e32 v174, v176
	v_permlane16_swap_b32_e32 v175, v177
	global_store_dwordx4 v[154:155], v[174:177], off offset:0 sc1
	s_waitcnt vmcnt(11)
	v_permlane16_swap_b32_e32 v178, v180
	v_permlane16_swap_b32_e32 v179, v181
	v_lshlrev_b32_e32 v246, 16, v178
	v_and_b32_e32 v247, 0xffff0000, v178
	v_lshlrev_b32_e32 v248, 16, v179
	v_and_b32_e32 v249, 0xffff0000, v179
	v_pk_mul_f32 v[246:247], v[38:39], v[246:247]
	v_pk_mul_f32 v[248:249], v[40:41], v[248:249]
	v_cvt_pk_bf16_f32 v178, v246, v247
	v_cvt_pk_bf16_f32 v179, v248, v249
	v_lshlrev_b32_e32 v246, 16, v180
	v_and_b32_e32 v247, 0xffff0000, v180
	v_lshlrev_b32_e32 v248, 16, v181
	v_and_b32_e32 v249, 0xffff0000, v181
	v_pk_mul_f32 v[246:247], v[34:35], v[246:247]
	v_pk_mul_f32 v[248:249], v[36:37], v[248:249]
	v_cvt_pk_bf16_f32 v180, v246, v247
	v_cvt_pk_bf16_f32 v181, v248, v249
	s_nop 1
	v_permlane16_swap_b32_e32 v178, v180
	v_permlane16_swap_b32_e32 v179, v181
	global_store_dwordx4 v[156:157], v[178:181], off offset:0 sc1
	s_waitcnt vmcnt(10)
	v_permlane16_swap_b32_e32 v182, v184
	v_permlane16_swap_b32_e32 v183, v185
	v_lshlrev_b32_e32 v246, 16, v182
	v_and_b32_e32 v247, 0xffff0000, v182
	v_lshlrev_b32_e32 v248, 16, v183
	v_and_b32_e32 v249, 0xffff0000, v183
	v_pk_mul_f32 v[246:247], v[30:31], v[246:247]
	v_pk_mul_f32 v[248:249], v[32:33], v[248:249]
	v_cvt_pk_bf16_f32 v182, v246, v247
	v_cvt_pk_bf16_f32 v183, v248, v249
	v_lshlrev_b32_e32 v246, 16, v184
	v_and_b32_e32 v247, 0xffff0000, v184
	v_lshlrev_b32_e32 v248, 16, v185
	v_and_b32_e32 v249, 0xffff0000, v185
	v_pk_mul_f32 v[246:247], v[26:27], v[246:247]
	v_pk_mul_f32 v[248:249], v[28:29], v[248:249]
	v_cvt_pk_bf16_f32 v184, v246, v247
	v_cvt_pk_bf16_f32 v185, v248, v249
	s_nop 1
	v_permlane16_swap_b32_e32 v182, v184
	v_permlane16_swap_b32_e32 v183, v185
	global_store_dwordx4 v[158:159], v[182:185], off offset:256 sc1
	s_waitcnt vmcnt(9)
	v_permlane16_swap_b32_e32 v186, v188
	v_permlane16_swap_b32_e32 v187, v189
	v_lshlrev_b32_e32 v246, 16, v186
	v_and_b32_e32 v247, 0xffff0000, v186
	v_lshlrev_b32_e32 v248, 16, v187
	v_and_b32_e32 v249, 0xffff0000, v187
	v_pk_mul_f32 v[246:247], v[22:23], v[246:247]
	v_pk_mul_f32 v[248:249], v[24:25], v[248:249]
	v_cvt_pk_bf16_f32 v186, v246, v247
	v_cvt_pk_bf16_f32 v187, v248, v249
	v_lshlrev_b32_e32 v246, 16, v188
	v_and_b32_e32 v247, 0xffff0000, v188
	v_lshlrev_b32_e32 v248, 16, v189
	v_and_b32_e32 v249, 0xffff0000, v189
	v_pk_mul_f32 v[246:247], v[18:19], v[246:247]
	v_pk_mul_f32 v[248:249], v[20:21], v[248:249]
	v_cvt_pk_bf16_f32 v188, v246, v247
	v_cvt_pk_bf16_f32 v189, v248, v249
	s_nop 1
	v_permlane16_swap_b32_e32 v186, v188
	v_permlane16_swap_b32_e32 v187, v189
	global_store_dwordx4 v[160:161], v[186:189], off offset:256 sc1
	s_waitcnt vmcnt(8)
	v_permlane16_swap_b32_e32 v190, v192
	v_permlane16_swap_b32_e32 v191, v193
	v_lshlrev_b32_e32 v246, 16, v190
	v_and_b32_e32 v247, 0xffff0000, v190
	v_lshlrev_b32_e32 v248, 16, v191
	v_and_b32_e32 v249, 0xffff0000, v191
	v_pk_mul_f32 v[246:247], v[14:15], v[246:247]
	v_pk_mul_f32 v[248:249], v[16:17], v[248:249]
	v_cvt_pk_bf16_f32 v190, v246, v247
	v_cvt_pk_bf16_f32 v191, v248, v249
	v_lshlrev_b32_e32 v246, 16, v192
	v_and_b32_e32 v247, 0xffff0000, v192
	v_lshlrev_b32_e32 v248, 16, v193
	v_and_b32_e32 v249, 0xffff0000, v193
	v_pk_mul_f32 v[246:247], v[10:11], v[246:247]
	v_pk_mul_f32 v[248:249], v[12:13], v[248:249]
	v_cvt_pk_bf16_f32 v192, v246, v247
	v_cvt_pk_bf16_f32 v193, v248, v249
	s_nop 1
	v_permlane16_swap_b32_e32 v190, v192
	v_permlane16_swap_b32_e32 v191, v193
	global_store_dwordx4 v[162:163], v[190:193], off offset:256 sc1
	s_waitcnt vmcnt(7)
	v_permlane16_swap_b32_e32 v194, v196
	v_permlane16_swap_b32_e32 v195, v197
	v_lshlrev_b32_e32 v246, 16, v194
	v_and_b32_e32 v247, 0xffff0000, v194
	v_lshlrev_b32_e32 v248, 16, v195
	v_and_b32_e32 v249, 0xffff0000, v195
	v_pk_mul_f32 v[246:247], v[6:7], v[246:247]
	v_pk_mul_f32 v[248:249], v[8:9], v[248:249]
	v_cvt_pk_bf16_f32 v194, v246, v247
	v_cvt_pk_bf16_f32 v195, v248, v249
	v_lshlrev_b32_e32 v246, 16, v196
	v_and_b32_e32 v247, 0xffff0000, v196
	v_lshlrev_b32_e32 v248, 16, v197
	v_and_b32_e32 v249, 0xffff0000, v197
	v_pk_mul_f32 v[246:247], v[2:3], v[246:247]
	v_pk_mul_f32 v[248:249], v[4:5], v[248:249]
	v_cvt_pk_bf16_f32 v196, v246, v247
	v_cvt_pk_bf16_f32 v197, v248, v249
	s_nop 1
	v_permlane16_swap_b32_e32 v194, v196
	v_permlane16_swap_b32_e32 v195, v197
	global_store_dwordx4 v[164:165], v[194:197], off offset:256 sc1
	s_branch .Lmix_done
.Lmix_pass1c:
	s_mov_b32 s42, 0x0
	v_lshl_add_u64 v[148:149], v[144:145], 0, s[42:43]
	global_load_dwordx4 v[166:169], v[148:149], off offset:0
	s_mov_b32 s42, 0x0
	v_lshl_add_u64 v[150:151], v[146:147], 0, s[42:43]
	global_load_dwordx4 v[198:201], v[150:151], off offset:0 sc1
	s_mov_b32 s42, 0x10000
	v_lshl_add_u64 v[148:149], v[144:145], 0, s[42:43]
	global_load_dwordx4 v[170:173], v[148:149], off offset:0
	s_mov_b32 s42, 0x8000
	v_lshl_add_u64 v[152:153], v[146:147], 0, s[42:43]
	global_load_dwordx4 v[202:205], v[152:153], off offset:0 sc1
	s_mov_b32 s42, 0x20000
	v_lshl_add_u64 v[148:149], v[144:145], 0, s[42:43]
	global_load_dwordx4 v[174:177], v[148:149], off offset:0
	s_mov_b32 s42, 0x10000
	v_lshl_add_u64 v[154:155], v[146:147], 0, s[42:43]
	global_load_dwordx4 v[206:209], v[154:155], off offset:0 sc1
	s_mov_b32 s42, 0x30000
	v_lshl_add_u64 v[148:149], v[144:145], 0, s[42:43]
	global_load_dwordx4 v[178:181], v[148:149], off offset:0
	s_mov_b32 s42, 0x18000
	v_lshl_add_u64 v[156:157], v[146:147], 0, s[42:43]
	global_load_dwordx4 v[226:229], v[156:157], off offset:0 sc1
	s_mov_b32 s42, 0x0
	v_lshl_add_u64 v[148:149], v[144:145], 0, s[42:43]
	global_load_dwordx4 v[182:185], v[148:149], off offset:256
	s_mov_b32 s42, 0x0
	v_lshl_add_u64 v[158:159], v[146:147], 0, s[42:43]
	global_load_dwordx4 v[230:233], v[158:159], off offset:256 sc1
	s_mov_b32 s42, 0x10000
	v_lshl_add_u64 v[148:149], v[144:145], 0, s[42:43]
	global_load_dwordx4 v[186:189], v[148:149], off offset:256
	s_mov_b32 s42, 0x8000
	v_lshl_add_u64 v[160:161], v[146:147], 0, s[42:43]
	global_load_dwordx4 v[234:237], v[160:161], off offset:256 sc1
	s_mov_b32 s42, 0x20000
	v_lshl_add_u64 v[148:149], v[144:145], 0, s[42:43]
	global_load_dwordx4 v[190:193], v[148:149], off offset:256
	s_mov_b32 s42, 0x10000
	v_lshl_add_u64 v[162:163], v[146:147], 0, s[42:43]
	global_load_dwordx4 v[238:241], v[162:163], off offset:256 sc1
	s_mov_b32 s42, 0x30000
	v_lshl_add_u64 v[148:149], v[144:145], 0, s[42:43]
	global_load_dwordx4 v[194:197], v[148:149], off offset:256
	s_mov_b32 s42, 0x18000
	v_lshl_add_u64 v[164:165], v[146:147], 0, s[42:43]
	global_load_dwordx4 v[242:245], v[164:165], off offset:256 sc1
	s_waitcnt vmcnt(14)
	v_permlane16_swap_b32_e32 v166, v168
	v_permlane16_swap_b32_e32 v167, v169
	v_permlane16_swap_b32_e32 v198, v200
	v_permlane16_swap_b32_e32 v199, v201
	v_lshlrev_b32_e32 v246, 16, v166
	v_and_b32_e32 v247, 0xffff0000, v166
	v_lshlrev_b32_e32 v248, 16, v167
	v_and_b32_e32 v249, 0xffff0000, v167
	v_pk_mul_f32 v[246:247], v[126:127], v[246:247]
	v_pk_mul_f32 v[248:249], v[128:129], v[248:249]
	v_lshlrev_b32_e32 v216, 16, v198
	v_and_b32_e32 v217, 0xffff0000, v198
	v_lshlrev_b32_e32 v220, 16, v199
	v_and_b32_e32 v221, 0xffff0000, v199
	v_pk_add_f32 v[246:247], v[246:247], v[216:217]
	v_pk_add_f32 v[248:249], v[248:249], v[220:221]
	v_cvt_pk_bf16_f32 v166, v246, v247
	v_cvt_pk_bf16_f32 v167, v248, v249
	v_lshlrev_b32_e32 v246, 16, v168
	v_and_b32_e32 v247, 0xffff0000, v168
	v_lshlrev_b32_e32 v248, 16, v169
	v_and_b32_e32 v249, 0xffff0000, v169
	v_pk_mul_f32 v[246:247], v[122:123], v[246:247]
	v_pk_mul_f32 v[248:249], v[124:125], v[248:249]
	v_lshlrev_b32_e32 v216, 16, v200
	v_and_b32_e32 v217, 0xffff0000, v200
	v_lshlrev_b32_e32 v220, 16, v201
	v_and_b32_e32 v221, 0xffff0000, v201
	v_pk_add_f32 v[246:247], v[246:247], v[216:217]
	v_pk_add_f32 v[248:249], v[248:249], v[220:221]
	v_cvt_pk_bf16_f32 v168, v246, v247
	v_cvt_pk_bf16_f32 v169, v248, v249
	s_nop 1
	v_permlane16_swap_b32_e32 v166, v168
	v_permlane16_swap_b32_e32 v167, v169
	global_store_dwordx4 v[150:151], v[166:169], off offset:0
	s_nop 0
	s_mov_b32 s42, 0x80000
	v_lshl_add_u64 v[148:149], v[144:145], 0, s[42:43]
	global_load_dwordx4 v[166:169], v[148:149], off offset:0
	s_mov_b32 s42, 0x40000
	v_lshl_add_u64 v[150:151], v[146:147], 0, s[42:43]
	global_load_dwordx4 v[198:201], v[150:151], off offset:0 sc1
	s_waitcnt vmcnt(15)
	v_permlane16_swap_b32_e32 v170, v172
	v_permlane16_swap_b32_e32 v171, v173
	v_permlane16_swap_b32_e32 v202, v204
	v_permlane16_swap_b32_e32 v203, v205
	v_lshlrev_b32_e32 v246, 16, v170
	v_and_b32_e32 v247, 0xffff0000, v170
	v_lshlrev_b32_e32 v248, 16, v171
	v_and_b32_e32 v249, 0xffff0000, v171
	v_pk_mul_f32 v[246:247], v[118:119], v[246:247]
	v_pk_mul_f32 v[248:249], v[120:121], v[248:249]
	v_lshlrev_b32_e32 v216, 16, v202
	v_and_b32_e32 v217, 0xffff0000, v202
	v_lshlrev_b32_e32 v220, 16, v203
	v_and_b32_e32 v221, 0xffff0000, v203
	v_pk_add_f32 v[246:247], v[246:247], v[216:217]
	v_pk_add_f32 v[248:249], v[248:249], v[220:221]
	v_cvt_pk_bf16_f32 v170, v246, v247
	v_cvt_pk_bf16_f32 v171, v248, v249
	v_lshlrev_b32_e32 v246, 16, v172
	v_and_b32_e32 v247, 0xffff0000, v172
	v_lshlrev_b32_e32 v248, 16, v173
	v_and_b32_e32 v249, 0xffff0000, v173
	v_pk_mul_f32 v[246:247], v[114:115], v[246:247]
	v_pk_mul_f32 v[248:249], v[116:117], v[248:249]
	v_lshlrev_b32_e32 v216, 16, v204
	v_and_b32_e32 v217, 0xffff0000, v204
	v_lshlrev_b32_e32 v220, 16, v205
	v_and_b32_e32 v221, 0xffff0000, v205
	v_pk_add_f32 v[246:247], v[246:247], v[216:217]
	v_pk_add_f32 v[248:249], v[248:249], v[220:221]
	v_cvt_pk_bf16_f32 v172, v246, v247
	v_cvt_pk_bf16_f32 v173, v248, v249
	s_nop 1
	v_permlane16_swap_b32_e32 v170, v172
	v_permlane16_swap_b32_e32 v171, v173
	global_store_dwordx4 v[152:153], v[170:173], off offset:0
	s_nop 0
	s_mov_b32 s42, 0x90000
	v_lshl_add_u64 v[148:149], v[144:145], 0, s[42:43]
	global_load_dwordx4 v[170:173], v[148:149], off offset:0
	s_mov_b32 s42, 0x48000
	v_lshl_add_u64 v[152:153], v[146:147], 0, s[42:43]
	global_load_dwordx4 v[202:205], v[152:153], off offset:0 sc1
	s_waitcnt vmcnt(16)
	v_permlane16_swap_b32_e32 v174, v176
	v_permlane16_swap_b32_e32 v175, v177
	v_permlane16_swap_b32_e32 v206, v208
	v_permlane16_swap_b32_e32 v207, v209
	v_lshlrev_b32_e32 v246, 16, v174
	v_and_b32_e32 v247, 0xffff0000, v174
	v_lshlrev_b32_e32 v248, 16, v175
	v_and_b32_e32 v249, 0xffff0000, v175
	v_pk_mul_f32 v[246:247], v[110:111], v[246:247]
	v_pk_mul_f32 v[248:249], v[112:113], v[248:249]
	v_lshlrev_b32_e32 v216, 16, v206
	v_and_b32_e32 v217, 0xffff0000, v206
	v_lshlrev_b32_e32 v220, 16, v207
	v_and_b32_e32 v221, 0xffff0000, v207
	v_pk_add_f32 v[246:247], v[246:247], v[216:217]
	v_pk_add_f32 v[248:249], v[248:249], v[220:221]
	v_cvt_pk_bf16_f32 v174, v246, v247
	v_cvt_pk_bf16_f32 v175, v248, v249
	v_lshlrev_b32_e32 v246, 16, v176
	v_and_b32_e32 v247, 0xffff0000, v176
	v_lshlrev_b32_e32 v248, 16, v177
	v_and_b32_e32 v249, 0xffff0000, v177
	v_pk_mul_f32 v[246:247], v[106:107], v[246:247]
	v_pk_mul_f32 v[248:249], v[108:109], v[248:249]
	v_lshlrev_b32_e32 v216, 16, v208
	v_and_b32_e32 v217, 0xffff0000, v208
	v_lshlrev_b32_e32 v220, 16, v209
	v_and_b32_e32 v221, 0xffff0000, v209
	v_pk_add_f32 v[246:247], v[246:247], v[216:217]
	v_pk_add_f32 v[248:249], v[248:249], v[220:221]
	v_cvt_pk_bf16_f32 v176, v246, v247
	v_cvt_pk_bf16_f32 v177, v248, v249
	s_nop 1
	v_permlane16_swap_b32_e32 v174, v176
	v_permlane16_swap_b32_e32 v175, v177
	global_store_dwordx4 v[154:155], v[174:177], off offset:0
	s_nop 0
	s_mov_b32 s42, 0xa0000
	v_lshl_add_u64 v[148:149], v[144:145], 0, s[42:43]
	global_load_dwordx4 v[174:177], v[148:149], off offset:0
	s_mov_b32 s42, 0x50000
	v_lshl_add_u64 v[154:155], v[146:147], 0, s[42:43]
	global_load_dwordx4 v[206:209], v[154:155], off offset:0 sc1
	s_waitcnt vmcnt(17)
	v_permlane16_swap_b32_e32 v178, v180
	v_permlane16_swap_b32_e32 v179, v181
	v_permlane16_swap_b32_e32 v226, v228
	v_permlane16_swap_b32_e32 v227, v229
	v_lshlrev_b32_e32 v246, 16, v178
	v_and_b32_e32 v247, 0xffff0000, v178
	v_lshlrev_b32_e32 v248, 16, v179
	v_and_b32_e32 v249, 0xffff0000, v179
	v_pk_mul_f32 v[246:247], v[102:103], v[246:247]
	v_pk_mul_f32 v[248:249], v[104:105], v[248:249]
	v_lshlrev_b32_e32 v216, 16, v226
	v_and_b32_e32 v217, 0xffff0000, v226
	v_lshlrev_b32_e32 v220, 16, v227
	v_and_b32_e32 v221, 0xffff0000, v227
	v_pk_add_f32 v[246:247], v[246:247], v[216:217]
	v_pk_add_f32 v[248:249], v[248:249], v[220:221]
	v_cvt_pk_bf16_f32 v178, v246, v247
	v_cvt_pk_bf16_f32 v179, v248, v249
	v_lshlrev_b32_e32 v246, 16, v180
	v_and_b32_e32 v247, 0xffff0000, v180
	v_lshlrev_b32_e32 v248, 16, v181
	v_and_b32_e32 v249, 0xffff0000, v181
	v_pk_mul_f32 v[246:247], v[98:99], v[246:247]
	v_pk_mul_f32 v[248:249], v[100:101], v[248:249]
	v_lshlrev_b32_e32 v216, 16, v228
	v_and_b32_e32 v217, 0xffff0000, v228
	v_lshlrev_b32_e32 v220, 16, v229
	v_and_b32_e32 v221, 0xffff0000, v229
	v_pk_add_f32 v[246:247], v[246:247], v[216:217]
	v_pk_add_f32 v[248:249], v[248:249], v[220:221]
	v_cvt_pk_bf16_f32 v180, v246, v247
	v_cvt_pk_bf16_f32 v181, v248, v249
	s_nop 1
	v_permlane16_swap_b32_e32 v178, v180
	v_permlane16_swap_b32_e32 v179, v181
	global_store_dwordx4 v[156:157], v[178:181], off offset:0
	s_nop 0
	s_mov_b32 s42, 0xb0000
	v_lshl_add_u64 v[148:149], v[144:145], 0, s[42:43]
	global_load_dwordx4 v[178:181], v[148:149], off offset:0
	s_mov_b32 s42, 0x58000
	v_lshl_add_u64 v[156:157], v[146:147], 0, s[42:43]
	global_load_dwordx4 v[226:229], v[156:157], off offset:0 sc1
	s_waitcnt vmcnt(18)
	v_permlane16_swap_b32_e32 v182, v184
	v_permlane16_swap_b32_e32 v183, v185
	v_permlane16_swap_b32_e32 v230, v232
	v_permlane16_swap_b32_e32 v231, v233
	v_lshlrev_b32_e32 v246, 16, v182
	v_and_b32_e32 v247, 0xffff0000, v182
	v_lshlrev_b32_e32 v248, 16, v183
	v_and_b32_e32 v249, 0xffff0000, v183
	v_pk_mul_f32 v[246:247], v[94:95], v[246:247]
	v_pk_mul_f32 v[248:249], v[96:97], v[248:249]
	v_lshlrev_b32_e32 v216, 16, v230
	v_and_b32_e32 v217, 0xffff0000, v230
	v_lshlrev_b32_e32 v220, 16, v231
	v_and_b32_e32 v221, 0xffff0000, v231
	v_pk_add_f32 v[246:247], v[246:247], v[216:217]
	v_pk_add_f32 v[248:249], v[248:249], v[220:221]
	v_cvt_pk_bf16_f32 v182, v246, v247
	v_cvt_pk_bf16_f32 v183, v248, v249
	v_lshlrev_b32_e32 v246, 16, v184
	v_and_b32_e32 v247, 0xffff0000, v184
	v_lshlrev_b32_e32 v248, 16, v185
	v_and_b32_e32 v249, 0xffff0000, v185
	v_pk_mul_f32 v[246:247], v[90:91], v[246:247]
	v_pk_mul_f32 v[248:249], v[92:93], v[248:249]
	v_lshlrev_b32_e32 v216, 16, v232
	v_and_b32_e32 v217, 0xffff0000, v232
	v_lshlrev_b32_e32 v220, 16, v233
	v_and_b32_e32 v221, 0xffff0000, v233
	v_pk_add_f32 v[246:247], v[246:247], v[216:217]
	v_pk_add_f32 v[248:249], v[248:249], v[220:221]
	v_cvt_pk_bf16_f32 v184, v246, v247
	v_cvt_pk_bf16_f32 v185, v248, v249
	s_nop 1
	v_permlane16_swap_b32_e32 v182, v184
	v_permlane16_swap_b32_e32 v183, v185
	global_store_dwordx4 v[158:159], v[182:185], off offset:256
	s_nop 0
	s_mov_b32 s42, 0x80000
	v_lshl_add_u64 v[148:149], v[144:145], 0, s[42:43]
	global_load_dwordx4 v[182:185], v[148:149], off offset:256
	s_mov_b32 s42, 0x40000
	v_lshl_add_u64 v[158:159], v[146:147], 0, s[42:43]
	global_load_dwordx4 v[230:233], v[158:159], off offset:256 sc1
	s_waitcnt vmcnt(19)
	v_permlane16_swap_b32_e32 v186, v188
	v_permlane16_swap_b32_e32 v187, v189
	v_permlane16_swap_b32_e32 v234, v236
	v_permlane16_swap_b32_e32 v235, v237
	v_lshlrev_b32_e32 v246, 16, v186
	v_and_b32_e32 v247, 0xffff0000, v186
	v_lshlrev_b32_e32 v248, 16, v187
	v_and_b32_e32 v249, 0xffff0000, v187
	v_pk_mul_f32 v[246:247], v[86:87], v[246:247]
	v_pk_mul_f32 v[248:249], v[88:89], v[248:249]
	v_lshlrev_b32_e32 v216, 16, v234
	v_and_b32_e32 v217, 0xffff0000, v234
	v_lshlrev_b32_e32 v220, 16, v235
	v_and_b32_e32 v221, 0xffff0000, v235
	v_pk_add_f32 v[246:247], v[246:247], v[216:217]
	v_pk_add_f32 v[248:249], v[248:249], v[220:221]
	v_cvt_pk_bf16_f32 v186, v246, v247
	v_cvt_pk_bf16_f32 v187, v248, v249
	v_lshlrev_b32_e32 v246, 16, v188
	v_and_b32_e32 v247, 0xffff0000, v188
	v_lshlrev_b32_e32 v248, 16, v189
	v_and_b32_e32 v249, 0xffff0000, v189
	v_pk_mul_f32 v[246:247], v[82:83], v[246:247]
	v_pk_mul_f32 v[248:249], v[84:85], v[248:249]
	v_lshlrev_b32_e32 v216, 16, v236
	v_and_b32_e32 v217, 0xffff0000, v236
	v_lshlrev_b32_e32 v220, 16, v237
	v_and_b32_e32 v221, 0xffff0000, v237
	v_pk_add_f32 v[246:247], v[246:247], v[216:217]
	v_pk_add_f32 v[248:249], v[248:249], v[220:221]
	v_cvt_pk_bf16_f32 v188, v246, v247
	v_cvt_pk_bf16_f32 v189, v248, v249
	s_nop 1
	v_permlane16_swap_b32_e32 v186, v188
	v_permlane16_swap_b32_e32 v187, v189
	global_store_dwordx4 v[160:161], v[186:189], off offset:256
	s_nop 0
	s_mov_b32 s42, 0x90000
	v_lshl_add_u64 v[148:149], v[144:145], 0, s[42:43]
	global_load_dwordx4 v[186:189], v[148:149], off offset:256
	s_mov_b32 s42, 0x48000
	v_lshl_add_u64 v[160:161], v[146:147], 0, s[42:43]
	global_load_dwordx4 v[234:237], v[160:161], off offset:256 sc1
	s_waitcnt vmcnt(20)
	v_permlane16_swap_b32_e32 v190, v192
	v_permlane16_swap_b32_e32 v191, v193
	v_permlane16_swap_b32_e32 v238, v240
	v_permlane16_swap_b32_e32 v239, v241
	v_lshlrev_b32_e32 v246, 16, v190
	v_and_b32_e32 v247, 0xffff0000, v190
	v_lshlrev_b32_e32 v248, 16, v191
	v_and_b32_e32 v249, 0xffff0000, v191
	v_pk_mul_f32 v[246:247], v[78:79], v[246:247]
	v_pk_mul_f32 v[248:249], v[80:81], v[248:249]
	v_lshlrev_b32_e32 v216, 16, v238
	v_and_b32_e32 v217, 0xffff0000, v238
	v_lshlrev_b32_e32 v220, 16, v239
	v_and_b32_e32 v221, 0xffff0000, v239
	v_pk_add_f32 v[246:247], v[246:247], v[216:217]
	v_pk_add_f32 v[248:249], v[248:249], v[220:221]
	v_cvt_pk_bf16_f32 v190, v246, v247
	v_cvt_pk_bf16_f32 v191, v248, v249
	v_lshlrev_b32_e32 v246, 16, v192
	v_and_b32_e32 v247, 0xffff0000, v192
	v_lshlrev_b32_e32 v248, 16, v193
	v_and_b32_e32 v249, 0xffff0000, v193
	v_pk_mul_f32 v[246:247], v[74:75], v[246:247]
	v_pk_mul_f32 v[248:249], v[76:77], v[248:249]
	v_lshlrev_b32_e32 v216, 16, v240
	v_and_b32_e32 v217, 0xffff0000, v240
	v_lshlrev_b32_e32 v220, 16, v241
	v_and_b32_e32 v221, 0xffff0000, v241
	v_pk_add_f32 v[246:247], v[246:247], v[216:217]
	v_pk_add_f32 v[248:249], v[248:249], v[220:221]
	v_cvt_pk_bf16_f32 v192, v246, v247
	v_cvt_pk_bf16_f32 v193, v248, v249
	s_nop 1
	v_permlane16_swap_b32_e32 v190, v192
	v_permlane16_swap_b32_e32 v191, v193
	global_store_dwordx4 v[162:163], v[190:193], off offset:256
	s_nop 0
	s_mov_b32 s42, 0xa0000
	v_lshl_add_u64 v[148:149], v[144:145], 0, s[42:43]
	global_load_dwordx4 v[190:193], v[148:149], off offset:256
	s_mov_b32 s42, 0x50000
	v_lshl_add_u64 v[162:163], v[146:147], 0, s[42:43]
	global_load_dwordx4 v[238:241], v[162:163], off offset:256 sc1
	s_waitcnt vmcnt(21)
	v_permlane16_swap_b32_e32 v194, v196
	v_permlane16_swap_b32_e32 v195, v197
	v_permlane16_swap_b32_e32 v242, v244
	v_permlane16_swap_b32_e32 v243, v245
	v_lshlrev_b32_e32 v246, 16, v194
	v_and_b32_e32 v247, 0xffff0000, v194
	v_lshlrev_b32_e32 v248, 16, v195
	v_and_b32_e32 v249, 0xffff0000, v195
	v_pk_mul_f32 v[246:247], v[70:71], v[246:247]
	v_pk_mul_f32 v[248:249], v[72:73], v[248:249]
	v_lshlrev_b32_e32 v216, 16, v242
	v_and_b32_e32 v217, 0xffff0000, v242
	v_lshlrev_b32_e32 v220, 16, v243
	v_and_b32_e32 v221, 0xffff0000, v243
	v_pk_add_f32 v[246:247], v[246:247], v[216:217]
	v_pk_add_f32 v[248:249], v[248:249], v[220:221]
	v_cvt_pk_bf16_f32 v194, v246, v247
	v_cvt_pk_bf16_f32 v195, v248, v249
	v_lshlrev_b32_e32 v246, 16, v196
	v_and_b32_e32 v247, 0xffff0000, v196
	v_lshlrev_b32_e32 v248, 16, v197
	v_and_b32_e32 v249, 0xffff0000, v197
	v_pk_mul_f32 v[246:247], v[66:67], v[246:247]
	v_pk_mul_f32 v[248:249], v[68:69], v[248:249]
	v_lshlrev_b32_e32 v216, 16, v244
	v_and_b32_e32 v217, 0xffff0000, v244
	v_lshlrev_b32_e32 v220, 16, v245
	v_and_b32_e32 v221, 0xffff0000, v245
	v_pk_add_f32 v[246:247], v[246:247], v[216:217]
	v_pk_add_f32 v[248:249], v[248:249], v[220:221]
	v_cvt_pk_bf16_f32 v196, v246, v247
	v_cvt_pk_bf16_f32 v197, v248, v249
	s_nop 1
	v_permlane16_swap_b32_e32 v194, v196
	v_permlane16_swap_b32_e32 v195, v197
	global_store_dwordx4 v[164:165], v[194:197], off offset:256
	s_nop 0
	s_mov_b32 s42, 0xb0000
	v_lshl_add_u64 v[148:149], v[144:145], 0, s[42:43]
	global_load_dwordx4 v[194:197], v[148:149], off offset:256
	s_mov_b32 s42, 0x58000
	v_lshl_add_u64 v[164:165], v[146:147], 0, s[42:43]
	global_load_dwordx4 v[242:245], v[164:165], off offset:256 sc1
	s_waitcnt vmcnt(21)
	v_permlane16_swap_b32_e32 v166, v168
	v_permlane16_swap_b32_e32 v167, v169
	v_permlane16_swap_b32_e32 v198, v200
	v_permlane16_swap_b32_e32 v199, v201
	v_lshlrev_b32_e32 v246, 16, v166
	v_and_b32_e32 v247, 0xffff0000, v166
	v_lshlrev_b32_e32 v248, 16, v167
	v_and_b32_e32 v249, 0xffff0000, v167
	v_pk_mul_f32 v[246:247], v[62:63], v[246:247]
	v_pk_mul_f32 v[248:249], v[64:65], v[248:249]
	v_lshlrev_b32_e32 v216, 16, v198
	v_and_b32_e32 v217, 0xffff0000, v198
	v_lshlrev_b32_e32 v220, 16, v199
	v_and_b32_e32 v221, 0xffff0000, v199
	v_pk_add_f32 v[246:247], v[246:247], v[216:217]
	v_pk_add_f32 v[248:249], v[248:249], v[220:221]
	v_cvt_pk_bf16_f32 v166, v246, v247
	v_cvt_pk_bf16_f32 v167, v248, v249
	v_lshlrev_b32_e32 v246, 16, v168
	v_and_b32_e32 v247, 0xffff0000, v168
	v_lshlrev_b32_e32 v248, 16, v169
	v_and_b32_e32 v249, 0xffff0000, v169
	v_pk_mul_f32 v[246:247], v[58:59], v[246:247]
	v_pk_mul_f32 v[248:249], v[60:61], v[248:249]
	v_lshlrev_b32_e32 v216, 16, v200
	v_and_b32_e32 v217, 0xffff0000, v200
	v_lshlrev_b32_e32 v220, 16, v201
	v_and_b32_e32 v221, 0xffff0000, v201
	v_pk_add_f32 v[246:247], v[246:247], v[216:217]
	v_pk_add_f32 v[248:249], v[248:249], v[220:221]
	v_cvt_pk_bf16_f32 v168, v246, v247
	v_cvt_pk_bf16_f32 v169, v248, v249
	s_nop 1
	v_permlane16_swap_b32_e32 v166, v168
	v_permlane16_swap_b32_e32 v167, v169
	global_store_dwordx4 v[150:151], v[166:169], off offset:0
	s_waitcnt vmcnt(19)
	v_permlane16_swap_b32_e32 v170, v172
	v_permlane16_swap_b32_e32 v171, v173
	v_permlane16_swap_b32_e32 v202, v204
	v_permlane16_swap_b32_e32 v203, v205
	v_lshlrev_b32_e32 v246, 16, v170
	v_and_b32_e32 v247, 0xffff0000, v170
	v_lshlrev_b32_e32 v248, 16, v171
	v_and_b32_e32 v249, 0xffff0000, v171
	v_pk_mul_f32 v[246:247], v[54:55], v[246:247]
	v_pk_mul_f32 v[248:249], v[56:57], v[248:249]
	v_lshlrev_b32_e32 v216, 16, v202
	v_and_b32_e32 v217, 0xffff0000, v202
	v_lshlrev_b32_e32 v220, 16, v203
	v_and_b32_e32 v221, 0xffff0000, v203
	v_pk_add_f32 v[246:247], v[246:247], v[216:217]
	v_pk_add_f32 v[248:249], v[248:249], v[220:221]
	v_cvt_pk_bf16_f32 v170, v246, v247
	v_cvt_pk_bf16_f32 v171, v248, v249
	v_lshlrev_b32_e32 v246, 16, v172
	v_and_b32_e32 v247, 0xffff0000, v172
	v_lshlrev_b32_e32 v248, 16, v173
	v_and_b32_e32 v249, 0xffff0000, v173
	v_pk_mul_f32 v[246:247], v[50:51], v[246:247]
	v_pk_mul_f32 v[248:249], v[52:53], v[248:249]
	v_lshlrev_b32_e32 v216, 16, v204
	v_and_b32_e32 v217, 0xffff0000, v204
	v_lshlrev_b32_e32 v220, 16, v205
	v_and_b32_e32 v221, 0xffff0000, v205
	v_pk_add_f32 v[246:247], v[246:247], v[216:217]
	v_pk_add_f32 v[248:249], v[248:249], v[220:221]
	v_cvt_pk_bf16_f32 v172, v246, v247
	v_cvt_pk_bf16_f32 v173, v248, v249
	s_nop 1
	v_permlane16_swap_b32_e32 v170, v172
	v_permlane16_swap_b32_e32 v171, v173
	global_store_dwordx4 v[152:153], v[170:173], off offset:0
	s_waitcnt vmcnt(17)
	v_permlane16_swap_b32_e32 v174, v176
	v_permlane16_swap_b32_e32 v175, v177
	v_permlane16_swap_b32_e32 v206, v208
	v_permlane16_swap_b32_e32 v207, v209
	v_lshlrev_b32_e32 v246, 16, v174
	v_and_b32_e32 v247, 0xffff0000, v174
	v_lshlrev_b32_e32 v248, 16, v175
	v_and_b32_e32 v249, 0xffff0000, v175
	v_pk_mul_f32 v[246:247], v[46:47], v[246:247]
	v_pk_mul_f32 v[248:249], v[48:49], v[248:249]
	v_lshlrev_b32_e32 v216, 16, v206
	v_and_b32_e32 v217, 0xffff0000, v206
	v_lshlrev_b32_e32 v220, 16, v207
	v_and_b32_e32 v221, 0xffff0000, v207
	v_pk_add_f32 v[246:247], v[246:247], v[216:217]
	v_pk_add_f32 v[248:249], v[248:249], v[220:221]
	v_cvt_pk_bf16_f32 v174, v246, v247
	v_cvt_pk_bf16_f32 v175, v248, v249
	v_lshlrev_b32_e32 v246, 16, v176
	v_and_b32_e32 v247, 0xffff0000, v176
	v_lshlrev_b32_e32 v248, 16, v177
	v_and_b32_e32 v249, 0xffff0000, v177
	v_pk_mul_f32 v[246:247], v[42:43], v[246:247]
	v_pk_mul_f32 v[248:249], v[44:45], v[248:249]
	v_lshlrev_b32_e32 v216, 16, v208
	v_and_b32_e32 v217, 0xffff0000, v208
	v_lshlrev_b32_e32 v220, 16, v209
	v_and_b32_e32 v221, 0xffff0000, v209
	v_pk_add_f32 v[246:247], v[246:247], v[216:217]
	v_pk_add_f32 v[248:249], v[248:249], v[220:221]
	v_cvt_pk_bf16_f32 v176, v246, v247
	v_cvt_pk_bf16_f32 v177, v248, v249
	s_nop 1
	v_permlane16_swap_b32_e32 v174, v176
	v_permlane16_swap_b32_e32 v175, v177
	global_store_dwordx4 v[154:155], v[174:177], off offset:0
	s_waitcnt vmcnt(15)
	v_permlane16_swap_b32_e32 v178, v180
	v_permlane16_swap_b32_e32 v179, v181
	v_permlane16_swap_b32_e32 v226, v228
	v_permlane16_swap_b32_e32 v227, v229
	v_lshlrev_b32_e32 v246, 16, v178
	v_and_b32_e32 v247, 0xffff0000, v178
	v_lshlrev_b32_e32 v248, 16, v179
	v_and_b32_e32 v249, 0xffff0000, v179
	v_pk_mul_f32 v[246:247], v[38:39], v[246:247]
	v_pk_mul_f32 v[248:249], v[40:41], v[248:249]
	v_lshlrev_b32_e32 v216, 16, v226
	v_and_b32_e32 v217, 0xffff0000, v226
	v_lshlrev_b32_e32 v220, 16, v227
	v_and_b32_e32 v221, 0xffff0000, v227
	v_pk_add_f32 v[246:247], v[246:247], v[216:217]
	v_pk_add_f32 v[248:249], v[248:249], v[220:221]
	v_cvt_pk_bf16_f32 v178, v246, v247
	v_cvt_pk_bf16_f32 v179, v248, v249
	v_lshlrev_b32_e32 v246, 16, v180
	v_and_b32_e32 v247, 0xffff0000, v180
	v_lshlrev_b32_e32 v248, 16, v181
	v_and_b32_e32 v249, 0xffff0000, v181
	v_pk_mul_f32 v[246:247], v[34:35], v[246:247]
	v_pk_mul_f32 v[248:249], v[36:37], v[248:249]
	v_lshlrev_b32_e32 v216, 16, v228
	v_and_b32_e32 v217, 0xffff0000, v228
	v_lshlrev_b32_e32 v220, 16, v229
	v_and_b32_e32 v221, 0xffff0000, v229
	v_pk_add_f32 v[246:247], v[246:247], v[216:217]
	v_pk_add_f32 v[248:249], v[248:249], v[220:221]
	v_cvt_pk_bf16_f32 v180, v246, v247
	v_cvt_pk_bf16_f32 v181, v248, v249
	s_nop 1
	v_permlane16_swap_b32_e32 v178, v180
	v_permlane16_swap_b32_e32 v179, v181
	global_store_dwordx4 v[156:157], v[178:181], off offset:0
	s_waitcnt vmcnt(13)
	v_permlane16_swap_b32_e32 v182, v184
	v_permlane16_swap_b32_e32 v183, v185
	v_permlane16_swap_b32_e32 v230, v232
	v_permlane16_swap_b32_e32 v231, v233
	v_lshlrev_b32_e32 v246, 16, v182
	v_and_b32_e32 v247, 0xffff0000, v182
	v_lshlrev_b32_e32 v248, 16, v183
	v_and_b32_e32 v249, 0xffff0000, v183
	v_pk_mul_f32 v[246:247], v[30:31], v[246:247]
	v_pk_mul_f32 v[248:249], v[32:33], v[248:249]
	v_lshlrev_b32_e32 v216, 16, v230
	v_and_b32_e32 v217, 0xffff0000, v230
	v_lshlrev_b32_e32 v220, 16, v231
	v_and_b32_e32 v221, 0xffff0000, v231
	v_pk_add_f32 v[246:247], v[246:247], v[216:217]
	v_pk_add_f32 v[248:249], v[248:249], v[220:221]
	v_cvt_pk_bf16_f32 v182, v246, v247
	v_cvt_pk_bf16_f32 v183, v248, v249
	v_lshlrev_b32_e32 v246, 16, v184
	v_and_b32_e32 v247, 0xffff0000, v184
	v_lshlrev_b32_e32 v248, 16, v185
	v_and_b32_e32 v249, 0xffff0000, v185
	v_pk_mul_f32 v[246:247], v[26:27], v[246:247]
	v_pk_mul_f32 v[248:249], v[28:29], v[248:249]
	v_lshlrev_b32_e32 v216, 16, v232
	v_and_b32_e32 v217, 0xffff0000, v232
	v_lshlrev_b32_e32 v220, 16, v233
	v_and_b32_e32 v221, 0xffff0000, v233
	v_pk_add_f32 v[246:247], v[246:247], v[216:217]
	v_pk_add_f32 v[248:249], v[248:249], v[220:221]
	v_cvt_pk_bf16_f32 v184, v246, v247
	v_cvt_pk_bf16_f32 v185, v248, v249
	s_nop 1
	v_permlane16_swap_b32_e32 v182, v184
	v_permlane16_swap_b32_e32 v183, v185
	global_store_dwordx4 v[158:159], v[182:185], off offset:256
	s_waitcnt vmcnt(11)
	v_permlane16_swap_b32_e32 v186, v188
	v_permlane16_swap_b32_e32 v187, v189
	v_permlane16_swap_b32_e32 v234, v236
	v_permlane16_swap_b32_e32 v235, v237
	v_lshlrev_b32_e32 v246, 16, v186
	v_and_b32_e32 v247, 0xffff0000, v186
	v_lshlrev_b32_e32 v248, 16, v187
	v_and_b32_e32 v249, 0xffff0000, v187
	v_pk_mul_f32 v[246:247], v[22:23], v[246:247]
	v_pk_mul_f32 v[248:249], v[24:25], v[248:249]
	v_lshlrev_b32_e32 v216, 16, v234
	v_and_b32_e32 v217, 0xffff0000, v234
	v_lshlrev_b32_e32 v220, 16, v235
	v_and_b32_e32 v221, 0xffff0000, v235
	v_pk_add_f32 v[246:247], v[246:247], v[216:217]
	v_pk_add_f32 v[248:249], v[248:249], v[220:221]
	v_cvt_pk_bf16_f32 v186, v246, v247
	v_cvt_pk_bf16_f32 v187, v248, v249
	v_lshlrev_b32_e32 v246, 16, v188
	v_and_b32_e32 v247, 0xffff0000, v188
	v_lshlrev_b32_e32 v248, 16, v189
	v_and_b32_e32 v249, 0xffff0000, v189
	v_pk_mul_f32 v[246:247], v[18:19], v[246:247]
	v_pk_mul_f32 v[248:249], v[20:21], v[248:249]
	v_lshlrev_b32_e32 v216, 16, v236
	v_and_b32_e32 v217, 0xffff0000, v236
	v_lshlrev_b32_e32 v220, 16, v237
	v_and_b32_e32 v221, 0xffff0000, v237
	v_pk_add_f32 v[246:247], v[246:247], v[216:217]
	v_pk_add_f32 v[248:249], v[248:249], v[220:221]
	v_cvt_pk_bf16_f32 v188, v246, v247
	v_cvt_pk_bf16_f32 v189, v248, v249
	s_nop 1
	v_permlane16_swap_b32_e32 v186, v188
	v_permlane16_swap_b32_e32 v187, v189
	global_store_dwordx4 v[160:161], v[186:189], off offset:256
	s_waitcnt vmcnt(9)
	v_permlane16_swap_b32_e32 v190, v192
	v_permlane16_swap_b32_e32 v191, v193
	v_permlane16_swap_b32_e32 v238, v240
	v_permlane16_swap_b32_e32 v239, v241
	v_lshlrev_b32_e32 v246, 16, v190
	v_and_b32_e32 v247, 0xffff0000, v190
	v_lshlrev_b32_e32 v248, 16, v191
	v_and_b32_e32 v249, 0xffff0000, v191
	v_pk_mul_f32 v[246:247], v[14:15], v[246:247]
	v_pk_mul_f32 v[248:249], v[16:17], v[248:249]
	v_lshlrev_b32_e32 v216, 16, v238
	v_and_b32_e32 v217, 0xffff0000, v238
	v_lshlrev_b32_e32 v220, 16, v239
	v_and_b32_e32 v221, 0xffff0000, v239
	v_pk_add_f32 v[246:247], v[246:247], v[216:217]
	v_pk_add_f32 v[248:249], v[248:249], v[220:221]
	v_cvt_pk_bf16_f32 v190, v246, v247
	v_cvt_pk_bf16_f32 v191, v248, v249
	v_lshlrev_b32_e32 v246, 16, v192
	v_and_b32_e32 v247, 0xffff0000, v192
	v_lshlrev_b32_e32 v248, 16, v193
	v_and_b32_e32 v249, 0xffff0000, v193
	v_pk_mul_f32 v[246:247], v[10:11], v[246:247]
	v_pk_mul_f32 v[248:249], v[12:13], v[248:249]
	v_lshlrev_b32_e32 v216, 16, v240
	v_and_b32_e32 v217, 0xffff0000, v240
	v_lshlrev_b32_e32 v220, 16, v241
	v_and_b32_e32 v221, 0xffff0000, v241
	v_pk_add_f32 v[246:247], v[246:247], v[216:217]
	v_pk_add_f32 v[248:249], v[248:249], v[220:221]
	v_cvt_pk_bf16_f32 v192, v246, v247
	v_cvt_pk_bf16_f32 v193, v248, v249
	s_nop 1
	v_permlane16_swap_b32_e32 v190, v192
	v_permlane16_swap_b32_e32 v191, v193
	global_store_dwordx4 v[162:163], v[190:193], off offset:256
	s_waitcnt vmcnt(7)
	v_permlane16_swap_b32_e32 v194, v196
	v_permlane16_swap_b32_e32 v195, v197
	v_permlane16_swap_b32_e32 v242, v244
	v_permlane16_swap_b32_e32 v243, v245
	v_lshlrev_b32_e32 v246, 16, v194
	v_and_b32_e32 v247, 0xffff0000, v194
	v_lshlrev_b32_e32 v248, 16, v195
	v_and_b32_e32 v249, 0xffff0000, v195
	v_pk_mul_f32 v[246:247], v[6:7], v[246:247]
	v_pk_mul_f32 v[248:249], v[8:9], v[248:249]
	v_lshlrev_b32_e32 v216, 16, v242
	v_and_b32_e32 v217, 0xffff0000, v242
	v_lshlrev_b32_e32 v220, 16, v243
	v_and_b32_e32 v221, 0xffff0000, v243
	v_pk_add_f32 v[246:247], v[246:247], v[216:217]
	v_pk_add_f32 v[248:249], v[248:249], v[220:221]
	v_cvt_pk_bf16_f32 v194, v246, v247
	v_cvt_pk_bf16_f32 v195, v248, v249
	v_lshlrev_b32_e32 v246, 16, v196
	v_and_b32_e32 v247, 0xffff0000, v196
	v_lshlrev_b32_e32 v248, 16, v197
	v_and_b32_e32 v249, 0xffff0000, v197
	v_pk_mul_f32 v[246:247], v[2:3], v[246:247]
	v_pk_mul_f32 v[248:249], v[4:5], v[248:249]
	v_lshlrev_b32_e32 v216, 16, v244
	v_and_b32_e32 v217, 0xffff0000, v244
	v_lshlrev_b32_e32 v220, 16, v245
	v_and_b32_e32 v221, 0xffff0000, v245
	v_pk_add_f32 v[246:247], v[246:247], v[216:217]
	v_pk_add_f32 v[248:249], v[248:249], v[220:221]
	v_cvt_pk_bf16_f32 v196, v246, v247
	v_cvt_pk_bf16_f32 v197, v248, v249
	s_nop 1
	v_permlane16_swap_b32_e32 v194, v196
	v_permlane16_swap_b32_e32 v195, v197
	global_store_dwordx4 v[164:165], v[194:197], off offset:256
.Lmix_done:
	s_cmp_lg_u32 s12, 0
	s_cbranch_scc1 .Lmixrb_b
	s_cmp_eq_u32 s27, 2
	s_cbranch_scc0 .Lmixrb_b
	v_readlane_b32 s18, v252, 34
	s_cmp_eq_u32 s18, 0x100
	s_cbranch_scc0 .Lmixrb_b
	s_waitcnt vmcnt(0)
	s_barrier
	v_cmp_eq_u32_e32 vcc, 0, v211
	s_and_saveexec_b64 s[20:21], vcc
	s_cbranch_execz .Lmixrb_b2
	v_readlane_b32 s18, v252, 61
	s_mul_i32 s18, s18, 0x420
	s_add_u32 s18, s18, 0x23f9a508
	s_add_u32 s22, s8, s18
	s_addc_u32 s23, s9, 0
	v_mov_b32_e32 v246, s22
	v_mov_b32_e32 v247, s23
	v_readlane_b32 s18, v251, 0
	s_lshl_b32 s18, 1, s18
	v_mov_b32_e32 v248, s18
	flat_atomic_or v[246:247], v248
	s_waitcnt vmcnt(0) lgkmcnt(0)
.Lmixrb_b2:
	s_or_b64 exec, exec, s[20:21]
.Lmixrb_b:
	s_add_i32 s27, s27, 1
	s_mov_b64 s[0:1], 0
	s_branch .LBB0_73
